# K-loops: no-op setprio 0/1 pairs inside MFMA blocks removed; P1 first load segment keeps all 16 ds_reads in flight
# speedup vs baseline: 1.0019x; 1.0019x over previous
; #define PG8_STAGE(bufoff, gbase, voff) do { _Pragma("unroll") for (int _i = 0; _i < 2; ++_i) \
;         __builtin_amdgcn_global_load_lds((const unsigned*)((const char*)(gbase) + (voff)[_i]), (PG8_LAS unsigned*)(lds + (bufoff) + ldsw + _i * 8192), 16, 0, 0); } while (0)
; #define PG8_LDA(dst, b, h) do { _Pragma("unroll") for (int m = 0; m < 4; ++m) _Pragma("unroll") for (int k = 0; k < 2; ++k) dst[m][k] = *(const PG8_LAS bf16x8*)(lds + PG8_SA(b, h) + aoff + m * 2048 + k * 1024); } while (0)
; #define PG8_LDB(dst, b, h) do { _Pragma("unroll") for (int n = 0; n < 2; ++n) _Pragma("unroll") for (int k = 0; k < 2; ++k) dst[n][k] = *(const PG8_LAS bf16x8*)(lds + PG8_SB(b, h) + boff + n * 2048 + k * 1024); } while (0)
; #define PG8_WAIT_V(n) asm volatile("s_waitcnt vmcnt(" #n ")" ::: "memory")
; #define PG8_WAIT_L(n) asm volatile("s_waitcnt lgkmcnt(" #n ")" ::: "memory")
; #define PG8_BAR __builtin_amdgcn_s_barrier()
; #define PG8_SCHED __builtin_amdgcn_sched_barrier(0)
; template <class Epi, class Sched, bool ALIGN_EPI = false, bool SP2 = false, bool SPLITK = false>
; __device__ __forceinline__ void gemm_phase(PG8_LAS unsigned char* lds, const Gemm g, const Sched& S, const Epi& E) {
;     ...
;         const char* nA = has_next ? (const char*)g.A + (size_t)nxt.pm * tstep : cA; const char* nB = has_next ? (const char*)g.Bt + (size_t)nxt.pn * tstep : cB;
;         for (int t = 0; t < nt; t += 2) {
;             const bool last = (t == nt - 2);
;             if constexpr (SPLITK) { if (t == nt1) E.mid(acc, cur, wr, wc, fr, fq); }
;             const char* a1 = PG8_TA(t + 1);
;             const char* a2 = last ? nA : PG8_TA(t + 2); const char* b2 = last ? nB : PG8_TB(t + 2);
;             const char* a3 = a2 + kstep; const char* b3 = b2 + kstep;
;             if (last && has_next) S.a_ready(nxt);
;             if constexpr (SP2) {
;             PG8_LDB(B0, 0, 0); PG8_LDB(B1, 0, 1); PG8_SCHED; PG8_LDA(At, 0, 0); PG8_STAGE(PG8_SA(1, 1), a1 + hstep, voffA);
;             PG8_WAIT_V(8); PG8_WAIT_L(0); PG8_BAR; PG8_MMA(0, 0, At, B0); PG8_MMA(0, 1, At, B1); PG8_BAR; PG8_SCHED;
;             PG8_LDA(At, 0, 1); PG8_STAGE(PG8_SB(0, 0), b2, voffB); PG8_STAGE(PG8_SB(0, 1), b2 + hstep, voffB); PG8_STAGE(PG8_SA(0, 0), a2, voffA);
;             PG8_WAIT_V(8); PG8_WAIT_L(0); PG8_BAR; PG8_MMA(1, 0, At, B0); PG8_MMA(1, 1, At, B1); PG8_BAR; PG8_SCHED;
.LBB0_165:
	s_add_u32 s35, s54, 0xfffc0080
	s_addc_u32 s43, s55, -1
	s_add_i32 s45, 0, 0x10000
	s_cmp_eq_u32 s25, 12
	s_cselect_b32 s49, s4, s43
	s_cselect_b32 s48, s12, s35
	s_cselect_b32 s47, s21, s24
	s_cselect_b32 s46, s22, s23
	s_add_i32 s35, 0, 0x14000
	v_add_u32_e32 v142, s45, v198
	v_add_u32_e32 v158, s35, v198
	ds_read_b128 v[130:133], v142
	ds_read_b128 v[134:137], v142 offset:1024
	ds_read_b128 v[138:141], v142 offset:2048
	ds_read_b128 v[142:145], v142 offset:3072
	ds_read_b128 v[146:149], v158
	ds_read_b128 v[150:153], v158 offset:1024
	ds_read_b128 v[154:157], v158 offset:2048
	ds_read_b128 v[158:161], v158 offset:3072
	s_add_i32 m0, s51, 0xc000
	ds_read_b128 v[162:165], v199
	ds_read_b128 v[178:181], v199 offset:1024
	ds_read_b128 v[182:185], v199 offset:2048
	ds_read_b128 v[186:189], v199 offset:3072
	ds_read_b128 v[190:193], v199 offset:4096
	ds_read_b128 v[200:203], v199 offset:5120
	ds_read_b128 v[204:207], v199 offset:6144
	ds_read_b128 v[208:211], v199 offset:7168
	global_load_lds_dwordx4 v174, s[54:55]
	s_add_i32 m0, s51, 0xe000
	s_nop 0
	global_load_lds_dwordx4 v176, s[54:55]
	s_waitcnt vmcnt(8)
	s_waitcnt lgkmcnt(0)
	s_barrier
	s_setprio 1
	s_waitcnt lgkmcnt(0)
	v_mfma_f32_16x16x32_bf16 v[126:129], v[130:133], v[162:165], v[126:129]
	v_mfma_f32_16x16x32_bf16 v[122:125], v[138:141], v[162:165], v[122:125]
	v_mfma_f32_16x16x32_bf16 v[114:117], v[130:133], v[182:185], v[114:117]
	v_mfma_f32_16x16x32_bf16 v[106:109], v[138:141], v[182:185], v[106:109]
	v_mfma_f32_16x16x32_bf16 v[98:101], v[130:133], v[190:193], v[98:101]
	v_mfma_f32_16x16x32_bf16 v[90:93], v[138:141], v[190:193], v[90:93]
	v_mfma_f32_16x16x32_bf16 v[82:85], v[130:133], v[204:207], v[82:85]
	v_mfma_f32_16x16x32_bf16 v[74:77], v[138:141], v[204:207], v[74:77]
	v_mfma_f32_16x16x32_bf16 v[126:129], v[134:137], v[178:181], v[126:129]
	v_mfma_f32_16x16x32_bf16 v[122:125], v[142:145], v[178:181], v[122:125]
	v_mfma_f32_16x16x32_bf16 v[114:117], v[134:137], v[186:189], v[114:117]
	v_mfma_f32_16x16x32_bf16 v[106:109], v[142:145], v[186:189], v[106:109]
	v_mfma_f32_16x16x32_bf16 v[98:101], v[134:137], v[200:203], v[98:101]
	v_mfma_f32_16x16x32_bf16 v[90:93], v[142:145], v[200:203], v[90:93]
	v_mfma_f32_16x16x32_bf16 v[82:85], v[134:137], v[208:211], v[82:85]
	v_mfma_f32_16x16x32_bf16 v[74:77], v[142:145], v[208:211], v[74:77]
	v_mfma_f32_16x16x32_bf16 v[118:121], v[146:149], v[162:165], v[118:121]
	v_mfma_f32_16x16x32_bf16 v[110:113], v[154:157], v[162:165], v[110:113]
	v_mfma_f32_16x16x32_bf16 v[102:105], v[146:149], v[182:185], v[102:105]
	v_mfma_f32_16x16x32_bf16 v[94:97], v[154:157], v[182:185], v[94:97]
	v_mfma_f32_16x16x32_bf16 v[86:89], v[146:149], v[190:193], v[86:89]
	v_mfma_f32_16x16x32_bf16 v[78:81], v[154:157], v[190:193], v[78:81]
	v_mfma_f32_16x16x32_bf16 v[70:73], v[146:149], v[204:207], v[70:73]
	v_mfma_f32_16x16x32_bf16 v[66:69], v[154:157], v[204:207], v[66:69]
	v_mfma_f32_16x16x32_bf16 v[118:121], v[150:153], v[178:181], v[118:121]
	v_mfma_f32_16x16x32_bf16 v[110:113], v[158:161], v[178:181], v[110:113]
	v_mfma_f32_16x16x32_bf16 v[102:105], v[150:153], v[186:189], v[102:105]
	v_mfma_f32_16x16x32_bf16 v[94:97], v[158:161], v[186:189], v[94:97]
	v_mfma_f32_16x16x32_bf16 v[86:89], v[150:153], v[200:203], v[86:89]
	v_mfma_f32_16x16x32_bf16 v[78:81], v[158:161], v[200:203], v[78:81]
	v_mfma_f32_16x16x32_bf16 v[70:73], v[150:153], v[208:211], v[70:73]
	v_mfma_f32_16x16x32_bf16 v[66:69], v[158:161], v[208:211], v[66:69]
	s_setprio 0
	s_barrier
	s_add_i32 s43, s45, s33
	s_mov_b32 m0, s43
	ds_read_b128 v[162:165], v199 offset:16384
	ds_read_b128 v[178:181], v199 offset:17408
	ds_read_b128 v[182:185], v199 offset:18432
	ds_read_b128 v[186:189], v199 offset:19456
	ds_read_b128 v[190:193], v199 offset:20480
	ds_read_b128 v[200:203], v199 offset:21504
	ds_read_b128 v[204:207], v199 offset:22528
	ds_read_b128 v[208:211], v199 offset:23552
	global_load_lds_dwordx4 v0, s[46:47]
	s_add_i32 m0, s43, 0x2000
	s_add_u32 s76, s46, 0x40000
	s_addc_u32 s77, s47, 0
	s_add_i32 s35, s35, s33
	global_load_lds_dwordx4 v172, s[46:47]
	s_mov_b32 m0, s35
	s_nop 0
	global_load_lds_dwordx4 v0, s[76:77]
	s_add_i32 m0, s35, 0x2000
	s_nop 0
	global_load_lds_dwordx4 v172, s[76:77]
	s_mov_b32 m0, s51
	s_nop 0
	global_load_lds_dwordx4 v168, s[48:49]
	s_mov_b32 m0, s53
	s_nop 0
	global_load_lds_dwordx4 v170, s[48:49]
	s_waitcnt vmcnt(8)
	s_waitcnt lgkmcnt(0)
	s_barrier
	s_setprio 1
	s_waitcnt lgkmcnt(0)
	v_mfma_f32_16x16x32_bf16 v[62:65], v[130:133], v[162:165], v[62:65]
	v_mfma_f32_16x16x32_bf16 v[58:61], v[138:141], v[162:165], v[58:61]
	v_mfma_f32_16x16x32_bf16 v[50:53], v[130:133], v[182:185], v[50:53]
	v_mfma_f32_16x16x32_bf16 v[42:45], v[138:141], v[182:185], v[42:45]
	v_mfma_f32_16x16x32_bf16 v[34:37], v[130:133], v[190:193], v[34:37]
	v_mfma_f32_16x16x32_bf16 v[26:29], v[138:141], v[190:193], v[26:29]
	v_mfma_f32_16x16x32_bf16 v[18:21], v[130:133], v[204:207], v[18:21]
	v_mfma_f32_16x16x32_bf16 v[10:13], v[138:141], v[204:207], v[10:13]
	v_mfma_f32_16x16x32_bf16 v[62:65], v[134:137], v[178:181], v[62:65]
	v_mfma_f32_16x16x32_bf16 v[58:61], v[142:145], v[178:181], v[58:61]
	v_mfma_f32_16x16x32_bf16 v[50:53], v[134:137], v[186:189], v[50:53]
	v_mfma_f32_16x16x32_bf16 v[42:45], v[142:145], v[186:189], v[42:45]
	v_mfma_f32_16x16x32_bf16 v[34:37], v[134:137], v[200:203], v[34:37]
	v_mfma_f32_16x16x32_bf16 v[26:29], v[142:145], v[200:203], v[26:29]
	v_mfma_f32_16x16x32_bf16 v[18:21], v[134:137], v[208:211], v[18:21]
	v_mfma_f32_16x16x32_bf16 v[10:13], v[142:145], v[208:211], v[10:13]
	v_mfma_f32_16x16x32_bf16 v[54:57], v[146:149], v[162:165], v[54:57]
	v_mfma_f32_16x16x32_bf16 v[46:49], v[154:157], v[162:165], v[46:49]
	v_mfma_f32_16x16x32_bf16 v[38:41], v[146:149], v[182:185], v[38:41]
	v_mfma_f32_16x16x32_bf16 v[30:33], v[154:157], v[182:185], v[30:33]
	v_mfma_f32_16x16x32_bf16 v[22:25], v[146:149], v[190:193], v[22:25]
	v_mfma_f32_16x16x32_bf16 v[14:17], v[154:157], v[190:193], v[14:17]
	v_mfma_f32_16x16x32_bf16 v[6:9], v[146:149], v[204:207], v[6:9]
	v_mfma_f32_16x16x32_bf16 v[2:5], v[154:157], v[204:207], v[2:5]
	v_mfma_f32_16x16x32_bf16 v[54:57], v[150:153], v[178:181], v[54:57]
	v_mfma_f32_16x16x32_bf16 v[46:49], v[158:161], v[178:181], v[46:49]
	v_mfma_f32_16x16x32_bf16 v[38:41], v[150:153], v[186:189], v[38:41]
	v_mfma_f32_16x16x32_bf16 v[30:33], v[158:161], v[186:189], v[30:33]
	v_mfma_f32_16x16x32_bf16 v[22:25], v[150:153], v[200:203], v[22:25]
	v_mfma_f32_16x16x32_bf16 v[14:17], v[158:161], v[200:203], v[14:17]
	v_mfma_f32_16x16x32_bf16 v[6:9], v[150:153], v[208:211], v[6:9]
	v_mfma_f32_16x16x32_bf16 v[2:5], v[158:161], v[208:211], v[2:5]
	s_setprio 0
	s_barrier
; #define PG8_STAGE(bufoff, gbase, voff) do { _Pragma("unroll") for (int _i = 0; _i < 2; ++_i) \
;         __builtin_amdgcn_global_load_lds((const unsigned*)((const char*)(gbase) + (voff)[_i]), (PG8_LAS unsigned*)(lds + (bufoff) + ldsw + _i * 8192), 16, 0, 0); } while (0)
; #define PG8_LDA(dst, b, h) do { _Pragma("unroll") for (int m = 0; m < 4; ++m) _Pragma("unroll") for (int k = 0; k < 2; ++k) dst[m][k] = *(const PG8_LAS bf16x8*)(lds + PG8_SA(b, h) + aoff + m * 2048 + k * 1024); } while (0)
; #define PG8_LDB(dst, b, h) do { _Pragma("unroll") for (int n = 0; n < 2; ++n) _Pragma("unroll") for (int k = 0; k < 2; ++k) dst[n][k] = *(const PG8_LAS bf16x8*)(lds + PG8_SB(b, h) + boff + n * 2048 + k * 1024); } while (0)
; #define PG8_MMA(ai, bj, At, Bt) do { __builtin_amdgcn_s_setprio(1); _Pragma("unroll") for (int m = 0; m < 4; ++m) _Pragma("unroll") for (int n = 0; n < 2; ++n) _Pragma("unroll") for (int k = 0; k < 2; ++k) \
;         acc[ai][bj][m][n] = __builtin_amdgcn_mfma_f32_16x16x32_bf16(Bt[n][k], At[m][k], acc[ai][bj][m][n], 0, 0, 0); __builtin_amdgcn_s_setprio(0); } while (0)
; #define PG8_WAIT_V(n) asm volatile("s_waitcnt vmcnt(" #n ")" ::: "memory")
; #define PG8_WAIT_L(n) asm volatile("s_waitcnt lgkmcnt(" #n ")" ::: "memory")
; #define PG8_BAR __builtin_amdgcn_s_barrier()
; #define PG8_SCHED __builtin_amdgcn_sched_barrier(0)
; template <class Epi, class Sched, bool ALIGN_EPI = false, bool SP2 = false, bool SPLITK = false>
; __device__ __forceinline__ void gemm_phase(PG8_LAS unsigned char* lds, const Gemm g, const Sched& S, const Epi& E) {
;     ...
;             PG8_LDB(B0, 1, 0); PG8_LDB(B1, 1, 1); PG8_SCHED; PG8_LDA(At, 1, 0); PG8_STAGE(PG8_SA(0, 1), a2 + hstep, voffA);
;             PG8_WAIT_V(8); PG8_WAIT_L(0); PG8_BAR; PG8_MMA(0, 0, At, B0); PG8_MMA(0, 1, At, B1); PG8_BAR; PG8_SCHED;
;             PG8_LDA(At, 1, 1); PG8_STAGE(PG8_SB(1, 0), b3, voffB); PG8_STAGE(PG8_SB(1, 1), b3 + hstep, voffB); PG8_STAGE(PG8_SA(1, 0), a3, voffA);
;             PG8_WAIT_V(8); PG8_WAIT_L(0); PG8_BAR; PG8_MMA(1, 0, At, B0); PG8_MMA(1, 1, At, B1); PG8_BAR; PG8_SCHED;
	s_add_i32 s35, 0, 0x18000
	s_add_i32 s43, 0, 0x1c000
	v_add_u32_e32 v142, s35, v198
	v_add_u32_e32 v158, s43, v198
	ds_read_b128 v[130:133], v142
	ds_read_b128 v[134:137], v142 offset:1024
	ds_read_b128 v[138:141], v142 offset:2048
	ds_read_b128 v[142:145], v142 offset:3072
	ds_read_b128 v[146:149], v158
	ds_read_b128 v[150:153], v158 offset:1024
	ds_read_b128 v[154:157], v158 offset:2048
	ds_read_b128 v[158:161], v158 offset:3072
	s_add_u32 s48, s48, 0x40000
	s_addc_u32 s49, s49, 0
	s_mov_b32 m0, s56
	ds_read_b128 v[162:165], v199 offset:32768
	ds_read_b128 v[178:181], v199 offset:33792
	ds_read_b128 v[182:185], v199 offset:34816
	ds_read_b128 v[186:189], v199 offset:35840
	ds_read_b128 v[190:193], v199 offset:36864
	ds_read_b128 v[200:203], v199 offset:37888
	ds_read_b128 v[204:207], v199 offset:38912
	ds_read_b128 v[208:211], v199 offset:39936
	global_load_lds_dwordx4 v168, s[48:49]
	s_mov_b32 m0, s57
	s_nop 0
	global_load_lds_dwordx4 v170, s[48:49]
	s_waitcnt vmcnt(8)
	s_waitcnt lgkmcnt(0)
	s_barrier
	s_setprio 1
	s_waitcnt lgkmcnt(0)
	v_mfma_f32_16x16x32_bf16 v[126:129], v[130:133], v[162:165], v[126:129]
	v_mfma_f32_16x16x32_bf16 v[122:125], v[138:141], v[162:165], v[122:125]
	v_mfma_f32_16x16x32_bf16 v[114:117], v[130:133], v[182:185], v[114:117]
	v_mfma_f32_16x16x32_bf16 v[106:109], v[138:141], v[182:185], v[106:109]
	v_mfma_f32_16x16x32_bf16 v[98:101], v[130:133], v[190:193], v[98:101]
	v_mfma_f32_16x16x32_bf16 v[90:93], v[138:141], v[190:193], v[90:93]
	v_mfma_f32_16x16x32_bf16 v[82:85], v[130:133], v[204:207], v[82:85]
	v_mfma_f32_16x16x32_bf16 v[74:77], v[138:141], v[204:207], v[74:77]
	v_mfma_f32_16x16x32_bf16 v[126:129], v[134:137], v[178:181], v[126:129]
	v_mfma_f32_16x16x32_bf16 v[122:125], v[142:145], v[178:181], v[122:125]
	v_mfma_f32_16x16x32_bf16 v[114:117], v[134:137], v[186:189], v[114:117]
	v_mfma_f32_16x16x32_bf16 v[106:109], v[142:145], v[186:189], v[106:109]
	v_mfma_f32_16x16x32_bf16 v[98:101], v[134:137], v[200:203], v[98:101]
	v_mfma_f32_16x16x32_bf16 v[90:93], v[142:145], v[200:203], v[90:93]
	v_mfma_f32_16x16x32_bf16 v[82:85], v[134:137], v[208:211], v[82:85]
	v_mfma_f32_16x16x32_bf16 v[74:77], v[142:145], v[208:211], v[74:77]
	v_mfma_f32_16x16x32_bf16 v[118:121], v[146:149], v[162:165], v[118:121]
	v_mfma_f32_16x16x32_bf16 v[110:113], v[154:157], v[162:165], v[110:113]
	v_mfma_f32_16x16x32_bf16 v[102:105], v[146:149], v[182:185], v[102:105]
	v_mfma_f32_16x16x32_bf16 v[94:97], v[154:157], v[182:185], v[94:97]
	v_mfma_f32_16x16x32_bf16 v[86:89], v[146:149], v[190:193], v[86:89]
	v_mfma_f32_16x16x32_bf16 v[78:81], v[154:157], v[190:193], v[78:81]
	v_mfma_f32_16x16x32_bf16 v[70:73], v[146:149], v[204:207], v[70:73]
	v_mfma_f32_16x16x32_bf16 v[66:69], v[154:157], v[204:207], v[66:69]
	v_mfma_f32_16x16x32_bf16 v[118:121], v[150:153], v[178:181], v[118:121]
	v_mfma_f32_16x16x32_bf16 v[110:113], v[158:161], v[178:181], v[110:113]
	v_mfma_f32_16x16x32_bf16 v[102:105], v[150:153], v[186:189], v[102:105]
	v_mfma_f32_16x16x32_bf16 v[94:97], v[158:161], v[186:189], v[94:97]
	v_mfma_f32_16x16x32_bf16 v[86:89], v[150:153], v[200:203], v[86:89]
	v_mfma_f32_16x16x32_bf16 v[78:81], v[158:161], v[200:203], v[78:81]
	v_mfma_f32_16x16x32_bf16 v[70:73], v[150:153], v[208:211], v[70:73]
	v_mfma_f32_16x16x32_bf16 v[66:69], v[158:161], v[208:211], v[66:69]
	s_setprio 0
	s_barrier
	s_add_i32 s35, s35, s33
	s_add_u32 s46, s46, 0x80
	s_addc_u32 s47, s47, 0
	s_mov_b32 m0, s35
	ds_read_b128 v[162:165], v199 offset:49152
	ds_read_b128 v[178:181], v199 offset:50176
	ds_read_b128 v[182:185], v199 offset:51200
	ds_read_b128 v[186:189], v199 offset:52224
	ds_read_b128 v[190:193], v199 offset:53248
	ds_read_b128 v[200:203], v199 offset:54272
	ds_read_b128 v[204:207], v199 offset:55296
	ds_read_b128 v[208:211], v199 offset:56320
	global_load_lds_dwordx4 v0, s[46:47]
	s_add_i32 m0, s35, 0x2000
	s_add_i32 s35, s43, s33
	global_load_lds_dwordx4 v172, s[46:47]
	s_add_u32 s46, s46, 0x40000
	s_addc_u32 s47, s47, 0
	s_mov_b32 m0, s35
	s_nop 0
	global_load_lds_dwordx4 v0, s[46:47]
	s_add_i32 m0, s35, 0x2000
	s_nop 0
	global_load_lds_dwordx4 v172, s[46:47]
	s_sub_u32 s76, s48, 0x3ff80
	s_subb_u32 s77, s49, 0
	s_mov_b32 m0, s58
	s_nop 0
	global_load_lds_dwordx4 v168, s[76:77]
	s_mov_b32 m0, s59
	s_nop 0
	global_load_lds_dwordx4 v170, s[76:77]
	s_waitcnt vmcnt(8)
	s_waitcnt lgkmcnt(0)
	s_barrier
	s_setprio 1
	s_waitcnt lgkmcnt(0)
	v_mfma_f32_16x16x32_bf16 v[62:65], v[130:133], v[162:165], v[62:65]
	v_mfma_f32_16x16x32_bf16 v[58:61], v[138:141], v[162:165], v[58:61]
	v_mfma_f32_16x16x32_bf16 v[50:53], v[130:133], v[182:185], v[50:53]
	v_mfma_f32_16x16x32_bf16 v[42:45], v[138:141], v[182:185], v[42:45]
	v_mfma_f32_16x16x32_bf16 v[34:37], v[130:133], v[190:193], v[34:37]
	v_mfma_f32_16x16x32_bf16 v[26:29], v[138:141], v[190:193], v[26:29]
	v_mfma_f32_16x16x32_bf16 v[18:21], v[130:133], v[204:207], v[18:21]
	v_mfma_f32_16x16x32_bf16 v[10:13], v[138:141], v[204:207], v[10:13]
	v_mfma_f32_16x16x32_bf16 v[62:65], v[134:137], v[178:181], v[62:65]
	v_mfma_f32_16x16x32_bf16 v[58:61], v[142:145], v[178:181], v[58:61]
	v_mfma_f32_16x16x32_bf16 v[50:53], v[134:137], v[186:189], v[50:53]
	v_mfma_f32_16x16x32_bf16 v[42:45], v[142:145], v[186:189], v[42:45]
	v_mfma_f32_16x16x32_bf16 v[34:37], v[134:137], v[200:203], v[34:37]
	v_mfma_f32_16x16x32_bf16 v[26:29], v[142:145], v[200:203], v[26:29]
	v_mfma_f32_16x16x32_bf16 v[18:21], v[134:137], v[208:211], v[18:21]
	v_mfma_f32_16x16x32_bf16 v[10:13], v[142:145], v[208:211], v[10:13]
	v_mfma_f32_16x16x32_bf16 v[54:57], v[146:149], v[162:165], v[54:57]
	v_mfma_f32_16x16x32_bf16 v[46:49], v[154:157], v[162:165], v[46:49]
	v_mfma_f32_16x16x32_bf16 v[38:41], v[146:149], v[182:185], v[38:41]
	v_mfma_f32_16x16x32_bf16 v[30:33], v[154:157], v[182:185], v[30:33]
	v_mfma_f32_16x16x32_bf16 v[22:25], v[146:149], v[190:193], v[22:25]
	v_mfma_f32_16x16x32_bf16 v[14:17], v[154:157], v[190:193], v[14:17]
	v_mfma_f32_16x16x32_bf16 v[6:9], v[146:149], v[204:207], v[6:9]
	v_mfma_f32_16x16x32_bf16 v[2:5], v[154:157], v[204:207], v[2:5]
	v_mfma_f32_16x16x32_bf16 v[54:57], v[150:153], v[178:181], v[54:57]
	v_mfma_f32_16x16x32_bf16 v[46:49], v[158:161], v[178:181], v[46:49]
	v_mfma_f32_16x16x32_bf16 v[38:41], v[150:153], v[186:189], v[38:41]
	v_mfma_f32_16x16x32_bf16 v[30:33], v[158:161], v[186:189], v[30:33]
	v_mfma_f32_16x16x32_bf16 v[22:25], v[150:153], v[200:203], v[22:25]
	v_mfma_f32_16x16x32_bf16 v[14:17], v[158:161], v[200:203], v[14:17]
	v_mfma_f32_16x16x32_bf16 v[6:9], v[150:153], v[208:211], v[6:9]
	v_mfma_f32_16x16x32_bf16 v[2:5], v[158:161], v[208:211], v[2:5]
	s_setprio 0
	s_barrier
	s_add_i32 s25, s25, 2
	s_add_u32 s54, s54, 0x100
	s_addc_u32 s55, s55, 0
	s_add_u32 s23, s23, 0x100
	s_addc_u32 s24, s24, 0
	s_cmp_gt_u32 s25, 13
	s_cbranch_scc0 .LBB0_165
	s_and_b64 vcc, exec, s[16:17]
	s_cbranch_vccz .LBB0_168
	s_barrier

; #define PG8_STAGE(bufoff, gbase, voff) do { _Pragma("unroll") for (int _i = 0; _i < 2; ++_i) \
;         __builtin_amdgcn_global_load_lds((const unsigned*)((const char*)(gbase) + (voff)[_i]), (PG8_LAS unsigned*)(lds + (bufoff) + ldsw + _i * 8192), 16, 0, 0); } while (0)
; #define PG8_LDA(dst, b, h) do { _Pragma("unroll") for (int m = 0; m < 4; ++m) _Pragma("unroll") for (int k = 0; k < 2; ++k) dst[m][k] = *(const PG8_LAS bf16x8*)(lds + PG8_SA(b, h) + aoff + m * 2048 + k * 1024); } while (0)
; #define PG8_LDB(dst, b, h) do { _Pragma("unroll") for (int n = 0; n < 2; ++n) _Pragma("unroll") for (int k = 0; k < 2; ++k) dst[n][k] = *(const PG8_LAS bf16x8*)(lds + PG8_SB(b, h) + boff + n * 2048 + k * 1024); } while (0)
; #define PG8_WAIT_V(n) asm volatile("s_waitcnt vmcnt(" #n ")" ::: "memory")
; #define PG8_WAIT_L(n) asm volatile("s_waitcnt lgkmcnt(" #n ")" ::: "memory")
; #define PG8_BAR __builtin_amdgcn_s_barrier()
; #define PG8_SCHED __builtin_amdgcn_sched_barrier(0)
; template <class Epi, class Sched, bool ALIGN_EPI = false, bool SP2 = false, bool SPLITK = false>
; __device__ __forceinline__ void gemm_phase(PG8_LAS unsigned char* lds, const Gemm g, const Sched& S, const Epi& E) {
;     ...
;         const char* nA = has_next ? (const char*)g.A + (size_t)nxt.pm * tstep : cA; const char* nB = has_next ? (const char*)g.Bt + (size_t)nxt.pn * tstep : cB;
;         for (int t = 0; t < nt; t += 2) {
;             const bool last = (t == nt - 2);
;             if constexpr (SPLITK) { if (t == nt1) E.mid(acc, cur, wr, wc, fr, fq); }
;             const char* a1 = PG8_TA(t + 1);
;             const char* a2 = last ? nA : PG8_TA(t + 2); const char* b2 = last ? nB : PG8_TB(t + 2);
;             const char* a3 = a2 + kstep; const char* b3 = b2 + kstep;
;             if (last && has_next) S.a_ready(nxt);
;             if constexpr (SP2) {
;             PG8_LDB(B0, 0, 0); PG8_LDB(B1, 0, 1); PG8_SCHED; PG8_LDA(At, 0, 0); PG8_STAGE(PG8_SA(1, 1), a1 + hstep, voffA);
;             PG8_WAIT_V(8); PG8_WAIT_L(0); PG8_BAR; PG8_MMA(0, 0, At, B0); PG8_MMA(0, 1, At, B1); PG8_BAR; PG8_SCHED;
;             PG8_LDA(At, 0, 1); PG8_STAGE(PG8_SB(0, 0), b2, voffB); PG8_STAGE(PG8_SB(0, 1), b2 + hstep, voffB); PG8_STAGE(PG8_SA(0, 0), a2, voffA);
;             PG8_WAIT_V(8); PG8_WAIT_L(0); PG8_BAR; PG8_MMA(1, 0, At, B0); PG8_MMA(1, 1, At, B1); PG8_BAR; PG8_SCHED;
.LBB0_510:
	s_add_u32 s46, s52, 0xfffc0080
	s_addc_u32 s47, s53, -1
	s_add_i32 s59, 0, 0x10000
	s_cmp_eq_u32 s58, 12
	s_cselect_b32 s49, s12, s47
	s_cselect_b32 s48, s19, s46
	s_cselect_b32 s47, s21, s45
	s_cselect_b32 s46, s35, s43
	s_add_i32 s68, 0, 0x14000
	v_add_u32_e32 v118, s59, v224
	v_add_u32_e32 v150, s68, v224
	ds_read_b128 v[82:85], v118
	ds_read_b128 v[94:97], v118 offset:1024
	ds_read_b128 v[106:109], v118 offset:2048
	ds_read_b128 v[118:121], v118 offset:3072
	ds_read_b128 v[130:133], v150
	ds_read_b128 v[142:145], v150 offset:1024
	ds_read_b128 v[146:149], v150 offset:2048
	ds_read_b128 v[150:153], v150 offset:3072
	s_add_i32 m0, s25, 0xc000
	ds_read_b128 v[162:165], v225
	ds_read_b128 v[166:169], v225 offset:1024
	ds_read_b128 v[170:173], v225 offset:2048
	ds_read_b128 v[174:177], v225 offset:3072
	ds_read_b128 v[178:181], v225 offset:4096
	ds_read_b128 v[182:185], v225 offset:5120
	ds_read_b128 v[186:189], v225 offset:6144
	ds_read_b128 v[190:193], v225 offset:7168
	global_load_lds_dwordx4 v200, s[52:53]
	s_add_i32 m0, s25, 0xe000
	s_nop 0
	global_load_lds_dwordx4 v202, s[52:53]
	s_waitcnt vmcnt(8)
	s_waitcnt lgkmcnt(0)
	s_barrier
	s_setprio 1
	s_waitcnt lgkmcnt(0)
	v_mfma_f32_16x16x32_bf16 v[158:161], v[82:85], v[162:165], v[158:161]
	v_mfma_f32_16x16x32_bf16 v[154:157], v[106:109], v[162:165], v[154:157]
	v_mfma_f32_16x16x32_bf16 v[126:129], v[82:85], v[170:173], v[126:129]
	v_mfma_f32_16x16x32_bf16 v[122:125], v[106:109], v[170:173], v[122:125]
	v_mfma_f32_16x16x32_bf16 v[102:105], v[82:85], v[178:181], v[102:105]
	v_mfma_f32_16x16x32_bf16 v[98:101], v[106:109], v[178:181], v[98:101]
	v_mfma_f32_16x16x32_bf16 v[78:81], v[82:85], v[186:189], v[78:81]
	v_mfma_f32_16x16x32_bf16 v[74:77], v[106:109], v[186:189], v[74:77]
	v_mfma_f32_16x16x32_bf16 v[158:161], v[94:97], v[166:169], v[158:161]
	v_mfma_f32_16x16x32_bf16 v[154:157], v[118:121], v[166:169], v[154:157]
	v_mfma_f32_16x16x32_bf16 v[126:129], v[94:97], v[174:177], v[126:129]
	v_mfma_f32_16x16x32_bf16 v[122:125], v[118:121], v[174:177], v[122:125]
	v_mfma_f32_16x16x32_bf16 v[102:105], v[94:97], v[182:185], v[102:105]
	v_mfma_f32_16x16x32_bf16 v[98:101], v[118:121], v[182:185], v[98:101]
	v_mfma_f32_16x16x32_bf16 v[78:81], v[94:97], v[190:193], v[78:81]
	v_mfma_f32_16x16x32_bf16 v[74:77], v[118:121], v[190:193], v[74:77]
	v_mfma_f32_16x16x32_bf16 v[138:141], v[130:133], v[162:165], v[138:141]
	v_mfma_f32_16x16x32_bf16 v[134:137], v[146:149], v[162:165], v[134:137]
	v_mfma_f32_16x16x32_bf16 v[114:117], v[130:133], v[170:173], v[114:117]
	v_mfma_f32_16x16x32_bf16 v[110:113], v[146:149], v[170:173], v[110:113]
	v_mfma_f32_16x16x32_bf16 v[90:93], v[130:133], v[178:181], v[90:93]
	v_mfma_f32_16x16x32_bf16 v[86:89], v[146:149], v[178:181], v[86:89]
	v_mfma_f32_16x16x32_bf16 v[70:73], v[130:133], v[186:189], v[70:73]
	v_mfma_f32_16x16x32_bf16 v[66:69], v[146:149], v[186:189], v[66:69]
	v_mfma_f32_16x16x32_bf16 v[138:141], v[142:145], v[166:169], v[138:141]
	v_mfma_f32_16x16x32_bf16 v[134:137], v[150:153], v[166:169], v[134:137]
	v_mfma_f32_16x16x32_bf16 v[114:117], v[142:145], v[174:177], v[114:117]
	v_mfma_f32_16x16x32_bf16 v[110:113], v[150:153], v[174:177], v[110:113]
	v_mfma_f32_16x16x32_bf16 v[90:93], v[142:145], v[182:185], v[90:93]
	v_mfma_f32_16x16x32_bf16 v[86:89], v[150:153], v[182:185], v[86:89]
	v_mfma_f32_16x16x32_bf16 v[70:73], v[142:145], v[190:193], v[70:73]
	v_mfma_f32_16x16x32_bf16 v[66:69], v[150:153], v[190:193], v[66:69]
	s_setprio 0
	s_barrier
	s_add_i32 s59, s59, s24
	s_mov_b32 m0, s59
	ds_read_b128 v[162:165], v225 offset:16384
	ds_read_b128 v[166:169], v225 offset:17408
	ds_read_b128 v[170:173], v225 offset:18432
	ds_read_b128 v[174:177], v225 offset:19456
	ds_read_b128 v[178:181], v225 offset:20480
	ds_read_b128 v[182:185], v225 offset:21504
	ds_read_b128 v[186:189], v225 offset:22528
	ds_read_b128 v[190:193], v225 offset:23552
	global_load_lds_dwordx4 v0, s[46:47]
	s_add_i32 m0, s59, 0x2000
	s_add_u32 s64, s46, 0x40000
	s_addc_u32 s65, s47, 0
	s_add_i32 s59, s68, s24
	global_load_lds_dwordx4 v198, s[46:47]
	s_mov_b32 m0, s59
	s_nop 0
	global_load_lds_dwordx4 v0, s[64:65]
	s_add_i32 m0, s59, 0x2000
	s_nop 0
	global_load_lds_dwordx4 v198, s[64:65]
	s_mov_b32 m0, s25
	s_nop 0
	global_load_lds_dwordx4 v194, s[48:49]
	s_mov_b32 m0, s33
	s_nop 0
	global_load_lds_dwordx4 v196, s[48:49]
	s_waitcnt vmcnt(8)
	s_waitcnt lgkmcnt(0)
	s_barrier
	s_setprio 1
	s_waitcnt lgkmcnt(0)
	v_mfma_f32_16x16x32_bf16 v[62:65], v[82:85], v[162:165], v[62:65]
	v_mfma_f32_16x16x32_bf16 v[58:61], v[106:109], v[162:165], v[58:61]
	v_mfma_f32_16x16x32_bf16 v[46:49], v[82:85], v[170:173], v[46:49]
	v_mfma_f32_16x16x32_bf16 v[42:45], v[106:109], v[170:173], v[42:45]
	v_mfma_f32_16x16x32_bf16 v[30:33], v[82:85], v[178:181], v[30:33]
	v_mfma_f32_16x16x32_bf16 v[26:29], v[106:109], v[178:181], v[26:29]
	v_mfma_f32_16x16x32_bf16 v[14:17], v[82:85], v[186:189], v[14:17]
	v_mfma_f32_16x16x32_bf16 v[10:13], v[106:109], v[186:189], v[10:13]
	v_mfma_f32_16x16x32_bf16 v[62:65], v[94:97], v[166:169], v[62:65]
	v_mfma_f32_16x16x32_bf16 v[58:61], v[118:121], v[166:169], v[58:61]
	v_mfma_f32_16x16x32_bf16 v[46:49], v[94:97], v[174:177], v[46:49]
	v_mfma_f32_16x16x32_bf16 v[42:45], v[118:121], v[174:177], v[42:45]
	v_mfma_f32_16x16x32_bf16 v[30:33], v[94:97], v[182:185], v[30:33]
	v_mfma_f32_16x16x32_bf16 v[26:29], v[118:121], v[182:185], v[26:29]
	v_mfma_f32_16x16x32_bf16 v[14:17], v[94:97], v[190:193], v[14:17]
	v_mfma_f32_16x16x32_bf16 v[10:13], v[118:121], v[190:193], v[10:13]
	v_mfma_f32_16x16x32_bf16 v[54:57], v[130:133], v[162:165], v[54:57]
	v_mfma_f32_16x16x32_bf16 v[50:53], v[146:149], v[162:165], v[50:53]
	v_mfma_f32_16x16x32_bf16 v[38:41], v[130:133], v[170:173], v[38:41]
	v_mfma_f32_16x16x32_bf16 v[34:37], v[146:149], v[170:173], v[34:37]
	v_mfma_f32_16x16x32_bf16 v[22:25], v[130:133], v[178:181], v[22:25]
	v_mfma_f32_16x16x32_bf16 v[18:21], v[146:149], v[178:181], v[18:21]
	v_mfma_f32_16x16x32_bf16 v[6:9], v[130:133], v[186:189], v[6:9]
	v_mfma_f32_16x16x32_bf16 v[2:5], v[146:149], v[186:189], v[2:5]
	v_mfma_f32_16x16x32_bf16 v[54:57], v[142:145], v[166:169], v[54:57]
	v_mfma_f32_16x16x32_bf16 v[50:53], v[150:153], v[166:169], v[50:53]
	v_mfma_f32_16x16x32_bf16 v[38:41], v[142:145], v[174:177], v[38:41]
	v_mfma_f32_16x16x32_bf16 v[34:37], v[150:153], v[174:177], v[34:37]
	v_mfma_f32_16x16x32_bf16 v[22:25], v[142:145], v[182:185], v[22:25]
	v_mfma_f32_16x16x32_bf16 v[18:21], v[150:153], v[182:185], v[18:21]
	v_mfma_f32_16x16x32_bf16 v[6:9], v[142:145], v[190:193], v[6:9]
	v_mfma_f32_16x16x32_bf16 v[2:5], v[150:153], v[190:193], v[2:5]
	s_setprio 0
	s_barrier
; #define PG8_STAGE(bufoff, gbase, voff) do { _Pragma("unroll") for (int _i = 0; _i < 2; ++_i) \
;         __builtin_amdgcn_global_load_lds((const unsigned*)((const char*)(gbase) + (voff)[_i]), (PG8_LAS unsigned*)(lds + (bufoff) + ldsw + _i * 8192), 16, 0, 0); } while (0)
; #define PG8_LDA(dst, b, h) do { _Pragma("unroll") for (int m = 0; m < 4; ++m) _Pragma("unroll") for (int k = 0; k < 2; ++k) dst[m][k] = *(const PG8_LAS bf16x8*)(lds + PG8_SA(b, h) + aoff + m * 2048 + k * 1024); } while (0)
; #define PG8_LDB(dst, b, h) do { _Pragma("unroll") for (int n = 0; n < 2; ++n) _Pragma("unroll") for (int k = 0; k < 2; ++k) dst[n][k] = *(const PG8_LAS bf16x8*)(lds + PG8_SB(b, h) + boff + n * 2048 + k * 1024); } while (0)
; #define PG8_MMA(ai, bj, At, Bt) do { __builtin_amdgcn_s_setprio(1); _Pragma("unroll") for (int m = 0; m < 4; ++m) _Pragma("unroll") for (int n = 0; n < 2; ++n) _Pragma("unroll") for (int k = 0; k < 2; ++k) \
;         acc[ai][bj][m][n] = __builtin_amdgcn_mfma_f32_16x16x32_bf16(Bt[n][k], At[m][k], acc[ai][bj][m][n], 0, 0, 0); __builtin_amdgcn_s_setprio(0); } while (0)
; #define PG8_WAIT_V(n) asm volatile("s_waitcnt vmcnt(" #n ")" ::: "memory")
; #define PG8_WAIT_L(n) asm volatile("s_waitcnt lgkmcnt(" #n ")" ::: "memory")
; #define PG8_BAR __builtin_amdgcn_s_barrier()
; #define PG8_SCHED __builtin_amdgcn_sched_barrier(0)
; template <class Epi, class Sched, bool ALIGN_EPI = false, bool SP2 = false, bool SPLITK = false>
; __device__ __forceinline__ void gemm_phase(PG8_LAS unsigned char* lds, const Gemm g, const Sched& S, const Epi& E) {
;     ...
;             PG8_LDB(B0, 1, 0); PG8_LDB(B1, 1, 1); PG8_SCHED; PG8_LDA(At, 1, 0); PG8_STAGE(PG8_SA(0, 1), a2 + hstep, voffA);
;             PG8_WAIT_V(8); PG8_WAIT_L(0); PG8_BAR; PG8_MMA(0, 0, At, B0); PG8_MMA(0, 1, At, B1); PG8_BAR; PG8_SCHED;
;             PG8_LDA(At, 1, 1); PG8_STAGE(PG8_SB(1, 0), b3, voffB); PG8_STAGE(PG8_SB(1, 1), b3 + hstep, voffB); PG8_STAGE(PG8_SA(1, 0), a3, voffA);
;             PG8_WAIT_V(8); PG8_WAIT_L(0); PG8_BAR; PG8_MMA(1, 0, At, B0); PG8_MMA(1, 1, At, B1); PG8_BAR; PG8_SCHED;
	s_add_i32 s59, 0, 0x18000
	s_add_i32 s64, 0, 0x1c000
	v_add_u32_e32 v118, s59, v224
	v_add_u32_e32 v150, s64, v224
	ds_read_b128 v[82:85], v118
	ds_read_b128 v[94:97], v118 offset:1024
	ds_read_b128 v[106:109], v118 offset:2048
	ds_read_b128 v[118:121], v118 offset:3072
	ds_read_b128 v[130:133], v150
	ds_read_b128 v[142:145], v150 offset:1024
	ds_read_b128 v[146:149], v150 offset:2048
	ds_read_b128 v[150:153], v150 offset:3072
	s_add_u32 vcc_lo, s48, 0x80
	s_addc_u32 vcc_hi, s49, 0
	s_add_u32 s48, s48, 0x40000
	s_addc_u32 s49, s49, 0
	s_mov_b32 m0, s50
	ds_read_b128 v[162:165], v225 offset:32768
	ds_read_b128 v[166:169], v225 offset:33792
	ds_read_b128 v[170:173], v225 offset:34816
	ds_read_b128 v[174:177], v225 offset:35840
	ds_read_b128 v[178:181], v225 offset:36864
	ds_read_b128 v[182:185], v225 offset:37888
	ds_read_b128 v[186:189], v225 offset:38912
	ds_read_b128 v[190:193], v225 offset:39936
	global_load_lds_dwordx4 v194, s[48:49]
	s_mov_b32 m0, s51
	s_nop 0
	global_load_lds_dwordx4 v196, s[48:49]
	s_waitcnt vmcnt(8)
	s_waitcnt lgkmcnt(0)
	s_barrier
	s_setprio 1
	s_waitcnt lgkmcnt(0)
	v_mfma_f32_16x16x32_bf16 v[158:161], v[82:85], v[162:165], v[158:161]
	v_mfma_f32_16x16x32_bf16 v[154:157], v[106:109], v[162:165], v[154:157]
	v_mfma_f32_16x16x32_bf16 v[126:129], v[82:85], v[170:173], v[126:129]
	v_mfma_f32_16x16x32_bf16 v[122:125], v[106:109], v[170:173], v[122:125]
	v_mfma_f32_16x16x32_bf16 v[102:105], v[82:85], v[178:181], v[102:105]
	v_mfma_f32_16x16x32_bf16 v[98:101], v[106:109], v[178:181], v[98:101]
	v_mfma_f32_16x16x32_bf16 v[78:81], v[82:85], v[186:189], v[78:81]
	v_mfma_f32_16x16x32_bf16 v[74:77], v[106:109], v[186:189], v[74:77]
	v_mfma_f32_16x16x32_bf16 v[158:161], v[94:97], v[166:169], v[158:161]
	v_mfma_f32_16x16x32_bf16 v[154:157], v[118:121], v[166:169], v[154:157]
	v_mfma_f32_16x16x32_bf16 v[126:129], v[94:97], v[174:177], v[126:129]
	v_mfma_f32_16x16x32_bf16 v[122:125], v[118:121], v[174:177], v[122:125]
	v_mfma_f32_16x16x32_bf16 v[102:105], v[94:97], v[182:185], v[102:105]
	v_mfma_f32_16x16x32_bf16 v[98:101], v[118:121], v[182:185], v[98:101]
	v_mfma_f32_16x16x32_bf16 v[78:81], v[94:97], v[190:193], v[78:81]
	v_mfma_f32_16x16x32_bf16 v[74:77], v[118:121], v[190:193], v[74:77]
	v_mfma_f32_16x16x32_bf16 v[138:141], v[130:133], v[162:165], v[138:141]
	v_mfma_f32_16x16x32_bf16 v[134:137], v[146:149], v[162:165], v[134:137]
	v_mfma_f32_16x16x32_bf16 v[114:117], v[130:133], v[170:173], v[114:117]
	v_mfma_f32_16x16x32_bf16 v[110:113], v[146:149], v[170:173], v[110:113]
	v_mfma_f32_16x16x32_bf16 v[90:93], v[130:133], v[178:181], v[90:93]
	v_mfma_f32_16x16x32_bf16 v[86:89], v[146:149], v[178:181], v[86:89]
	v_mfma_f32_16x16x32_bf16 v[70:73], v[130:133], v[186:189], v[70:73]
	v_mfma_f32_16x16x32_bf16 v[66:69], v[146:149], v[186:189], v[66:69]
	v_mfma_f32_16x16x32_bf16 v[138:141], v[142:145], v[166:169], v[138:141]
	v_mfma_f32_16x16x32_bf16 v[134:137], v[150:153], v[166:169], v[134:137]
	v_mfma_f32_16x16x32_bf16 v[114:117], v[142:145], v[174:177], v[114:117]
	v_mfma_f32_16x16x32_bf16 v[110:113], v[150:153], v[174:177], v[110:113]
	v_mfma_f32_16x16x32_bf16 v[90:93], v[142:145], v[182:185], v[90:93]
	v_mfma_f32_16x16x32_bf16 v[86:89], v[150:153], v[182:185], v[86:89]
	v_mfma_f32_16x16x32_bf16 v[70:73], v[142:145], v[190:193], v[70:73]
	v_mfma_f32_16x16x32_bf16 v[66:69], v[150:153], v[190:193], v[66:69]
	s_setprio 0
	s_barrier
	s_add_i32 s48, s59, s24
	s_add_u32 s46, s46, 0x80
	s_addc_u32 s47, s47, 0
	s_mov_b32 m0, s48
	ds_read_b128 v[162:165], v225 offset:49152
	ds_read_b128 v[166:169], v225 offset:50176
	ds_read_b128 v[170:173], v225 offset:51200
	ds_read_b128 v[174:177], v225 offset:52224
	ds_read_b128 v[178:181], v225 offset:53248
	ds_read_b128 v[182:185], v225 offset:54272
	ds_read_b128 v[186:189], v225 offset:55296
	ds_read_b128 v[190:193], v225 offset:56320
	global_load_lds_dwordx4 v0, s[46:47]
	s_add_i32 m0, s48, 0x2000
	s_add_i32 s48, s64, s24
	global_load_lds_dwordx4 v198, s[46:47]
	s_add_u32 s46, s46, 0x40000
	s_addc_u32 s47, s47, 0
	s_mov_b32 m0, s48
	s_nop 0
	global_load_lds_dwordx4 v0, s[46:47]
	s_add_i32 m0, s48, 0x2000
	s_nop 0
	global_load_lds_dwordx4 v198, s[46:47]
	s_mov_b32 m0, s54
	s_nop 0
	global_load_lds_dwordx4 v194, vcc
	s_mov_b32 m0, s55
	s_nop 0
	global_load_lds_dwordx4 v196, vcc
	s_waitcnt vmcnt(8)
	s_waitcnt lgkmcnt(0)
	s_barrier
	s_setprio 1
	s_waitcnt lgkmcnt(0)
	v_mfma_f32_16x16x32_bf16 v[62:65], v[82:85], v[162:165], v[62:65]
	v_mfma_f32_16x16x32_bf16 v[58:61], v[106:109], v[162:165], v[58:61]
	v_mfma_f32_16x16x32_bf16 v[46:49], v[82:85], v[170:173], v[46:49]
	v_mfma_f32_16x16x32_bf16 v[42:45], v[106:109], v[170:173], v[42:45]
	v_mfma_f32_16x16x32_bf16 v[30:33], v[82:85], v[178:181], v[30:33]
	v_mfma_f32_16x16x32_bf16 v[26:29], v[106:109], v[178:181], v[26:29]
	v_mfma_f32_16x16x32_bf16 v[14:17], v[82:85], v[186:189], v[14:17]
	v_mfma_f32_16x16x32_bf16 v[10:13], v[106:109], v[186:189], v[10:13]
	v_mfma_f32_16x16x32_bf16 v[62:65], v[94:97], v[166:169], v[62:65]
	v_mfma_f32_16x16x32_bf16 v[58:61], v[118:121], v[166:169], v[58:61]
	v_mfma_f32_16x16x32_bf16 v[46:49], v[94:97], v[174:177], v[46:49]
	v_mfma_f32_16x16x32_bf16 v[42:45], v[118:121], v[174:177], v[42:45]
	v_mfma_f32_16x16x32_bf16 v[30:33], v[94:97], v[182:185], v[30:33]
	v_mfma_f32_16x16x32_bf16 v[26:29], v[118:121], v[182:185], v[26:29]
	v_mfma_f32_16x16x32_bf16 v[14:17], v[94:97], v[190:193], v[14:17]
	v_mfma_f32_16x16x32_bf16 v[10:13], v[118:121], v[190:193], v[10:13]
	v_mfma_f32_16x16x32_bf16 v[54:57], v[130:133], v[162:165], v[54:57]
	v_mfma_f32_16x16x32_bf16 v[50:53], v[146:149], v[162:165], v[50:53]
	v_mfma_f32_16x16x32_bf16 v[38:41], v[130:133], v[170:173], v[38:41]
	v_mfma_f32_16x16x32_bf16 v[34:37], v[146:149], v[170:173], v[34:37]
	v_mfma_f32_16x16x32_bf16 v[22:25], v[130:133], v[178:181], v[22:25]
	v_mfma_f32_16x16x32_bf16 v[18:21], v[146:149], v[178:181], v[18:21]
	v_mfma_f32_16x16x32_bf16 v[6:9], v[130:133], v[186:189], v[6:9]
	v_mfma_f32_16x16x32_bf16 v[2:5], v[146:149], v[186:189], v[2:5]
	v_mfma_f32_16x16x32_bf16 v[54:57], v[142:145], v[166:169], v[54:57]
	v_mfma_f32_16x16x32_bf16 v[50:53], v[150:153], v[166:169], v[50:53]
	v_mfma_f32_16x16x32_bf16 v[38:41], v[142:145], v[174:177], v[38:41]
	v_mfma_f32_16x16x32_bf16 v[34:37], v[150:153], v[174:177], v[34:37]
	v_mfma_f32_16x16x32_bf16 v[22:25], v[142:145], v[182:185], v[22:25]
	v_mfma_f32_16x16x32_bf16 v[18:21], v[150:153], v[182:185], v[18:21]
	v_mfma_f32_16x16x32_bf16 v[6:9], v[142:145], v[190:193], v[6:9]
	v_mfma_f32_16x16x32_bf16 v[2:5], v[150:153], v[190:193], v[2:5]
	s_setprio 0
	s_barrier
	s_add_i32 s58, s58, 2
	s_add_u32 s52, s52, 0x100
	s_addc_u32 s53, s53, 0
	s_add_u32 s43, s43, 0x100
	s_addc_u32 s45, s45, 0
	s_cmp_gt_u32 s58, 13
	s_cbranch_scc0 .LBB0_510
	s_and_b64 vcc, exec, s[16:17]
	s_cbranch_vccz .LBB0_513
	s_barrier

; #define PG8_STAGE(bufoff, gbase, voff) do { _Pragma("unroll") for (int _i = 0; _i < 2; ++_i) \
;         __builtin_amdgcn_global_load_lds((const unsigned*)((const char*)(gbase) + (voff)[_i]), (PG8_LAS unsigned*)(lds + (bufoff) + ldsw + _i * 8192), 16, 0, 0); } while (0)
; #define PG8_LDA(dst, b, h) do { _Pragma("unroll") for (int m = 0; m < 4; ++m) _Pragma("unroll") for (int k = 0; k < 2; ++k) dst[m][k] = *(const PG8_LAS bf16x8*)(lds + PG8_SA(b, h) + aoff + m * 2048 + k * 1024); } while (0)
; #define PG8_LDB(dst, b, h) do { _Pragma("unroll") for (int n = 0; n < 2; ++n) _Pragma("unroll") for (int k = 0; k < 2; ++k) dst[n][k] = *(const PG8_LAS bf16x8*)(lds + PG8_SB(b, h) + boff + n * 2048 + k * 1024); } while (0)
; #define PG8_WAIT_V(n) asm volatile("s_waitcnt vmcnt(" #n ")" ::: "memory")
; #define PG8_WAIT_L(n) asm volatile("s_waitcnt lgkmcnt(" #n ")" ::: "memory")
; #define PG8_BAR __builtin_amdgcn_s_barrier()
; #define PG8_SCHED __builtin_amdgcn_sched_barrier(0)
; template <class Epi, class Sched, bool ALIGN_EPI = false, bool SP2 = false, bool SPLITK = false>
; __device__ __forceinline__ void gemm_phase(PG8_LAS unsigned char* lds, const Gemm g, const Sched& S, const Epi& E) {
;     ...
;         const char* nA = has_next ? (const char*)g.A + (size_t)nxt.pm * tstep : cA; const char* nB = has_next ? (const char*)g.Bt + (size_t)nxt.pn * tstep : cB;
;         for (int t = 0; t < nt; t += 2) {
;             const bool last = (t == nt - 2);
;             if constexpr (SPLITK) { if (t == nt1) E.mid(acc, cur, wr, wc, fr, fq); }
;             const char* a1 = PG8_TA(t + 1);
;             const char* a2 = last ? nA : PG8_TA(t + 2); const char* b2 = last ? nB : PG8_TB(t + 2);
;             const char* a3 = a2 + kstep; const char* b3 = b2 + kstep;
;             if (last && has_next) S.a_ready(nxt);
;             if constexpr (SP2) {
;             PG8_LDB(B0, 0, 0); PG8_LDB(B1, 0, 1); PG8_SCHED; PG8_LDA(At, 0, 0); PG8_STAGE(PG8_SA(1, 1), a1 + hstep, voffA);
;             PG8_WAIT_V(8); PG8_WAIT_L(0); PG8_BAR; PG8_MMA(0, 0, At, B0); PG8_MMA(0, 1, At, B1); PG8_BAR; PG8_SCHED;
;             PG8_LDA(At, 0, 1); PG8_STAGE(PG8_SB(0, 0), b2, voffB); PG8_STAGE(PG8_SB(0, 1), b2 + hstep, voffB); PG8_STAGE(PG8_SA(0, 0), a2, voffA);
;             PG8_WAIT_V(8); PG8_WAIT_L(0); PG8_BAR; PG8_MMA(1, 0, At, B0); PG8_MMA(1, 1, At, B1); PG8_BAR; PG8_SCHED;
.LBB0_582:
	s_add_u32 s46, s42, 0xfffc0080
	s_addc_u32 s47, s43, -1
	s_add_i32 s64, 0, 0x10000
	s_cmp_eq_u32 s45, 12
	s_cselect_b32 s49, s4, s47
	s_cselect_b32 s48, s12, s46
	s_cselect_b32 s47, s19, s41
	s_cselect_b32 s46, s21, s25
	s_add_i32 s68, 0, 0x14000
	v_add_u32_e32 v142, s64, v181
	v_add_u32_e32 v168, s68, v181
	ds_read_b128 v[130:133], v142
	ds_read_b128 v[134:137], v142 offset:1024
	ds_read_b128 v[138:141], v142 offset:2048
	ds_read_b128 v[142:145], v142 offset:3072
	ds_read_b128 v[156:159], v168
	ds_read_b128 v[160:163], v168 offset:1024
	ds_read_b128 v[164:167], v168 offset:2048
	ds_read_b128 v[170:173], v168 offset:3072
	s_add_i32 m0, s51, 0xc000
	ds_read_b128 v[176:179], v186
	ds_read_b128 v[182:185], v186 offset:1024
	ds_read_b128 v[188:191], v186 offset:2048
	ds_read_b128 v[192:195], v186 offset:3072
	ds_read_b128 v[196:199], v186 offset:4096
	ds_read_b128 v[200:203], v186 offset:5120
	ds_read_b128 v[204:207], v186 offset:6144
	ds_read_b128 v[208:211], v186 offset:7168
	global_load_lds_dwordx4 v152, s[42:43]
	s_add_i32 m0, s51, 0xe000
	s_nop 0
	global_load_lds_dwordx4 v154, s[42:43]
	s_waitcnt vmcnt(8)
	s_waitcnt lgkmcnt(0)
	s_barrier
	s_setprio 1
	s_waitcnt lgkmcnt(0)
	v_mfma_f32_16x16x32_bf16 v[126:129], v[130:133], v[176:179], v[126:129]
	v_mfma_f32_16x16x32_bf16 v[118:121], v[138:141], v[176:179], v[118:121]
	v_mfma_f32_16x16x32_bf16 v[110:113], v[130:133], v[188:191], v[110:113]
	v_mfma_f32_16x16x32_bf16 v[102:105], v[138:141], v[188:191], v[102:105]
	v_mfma_f32_16x16x32_bf16 v[94:97], v[130:133], v[196:199], v[94:97]
	v_mfma_f32_16x16x32_bf16 v[86:89], v[138:141], v[196:199], v[86:89]
	v_mfma_f32_16x16x32_bf16 v[78:81], v[130:133], v[204:207], v[78:81]
	v_mfma_f32_16x16x32_bf16 v[70:73], v[138:141], v[204:207], v[70:73]
	v_mfma_f32_16x16x32_bf16 v[126:129], v[134:137], v[182:185], v[126:129]
	v_mfma_f32_16x16x32_bf16 v[118:121], v[142:145], v[182:185], v[118:121]
	v_mfma_f32_16x16x32_bf16 v[110:113], v[134:137], v[192:195], v[110:113]
	v_mfma_f32_16x16x32_bf16 v[102:105], v[142:145], v[192:195], v[102:105]
	v_mfma_f32_16x16x32_bf16 v[94:97], v[134:137], v[200:203], v[94:97]
	v_mfma_f32_16x16x32_bf16 v[86:89], v[142:145], v[200:203], v[86:89]
	v_mfma_f32_16x16x32_bf16 v[78:81], v[134:137], v[208:211], v[78:81]
	v_mfma_f32_16x16x32_bf16 v[70:73], v[142:145], v[208:211], v[70:73]
	v_mfma_f32_16x16x32_bf16 v[122:125], v[156:159], v[176:179], v[122:125]
	v_mfma_f32_16x16x32_bf16 v[114:117], v[164:167], v[176:179], v[114:117]
	v_mfma_f32_16x16x32_bf16 v[106:109], v[156:159], v[188:191], v[106:109]
	v_mfma_f32_16x16x32_bf16 v[98:101], v[164:167], v[188:191], v[98:101]
	v_mfma_f32_16x16x32_bf16 v[90:93], v[156:159], v[196:199], v[90:93]
	v_mfma_f32_16x16x32_bf16 v[82:85], v[164:167], v[196:199], v[82:85]
	v_mfma_f32_16x16x32_bf16 v[74:77], v[156:159], v[204:207], v[74:77]
	v_mfma_f32_16x16x32_bf16 v[66:69], v[164:167], v[204:207], v[66:69]
	v_mfma_f32_16x16x32_bf16 v[122:125], v[160:163], v[182:185], v[122:125]
	v_mfma_f32_16x16x32_bf16 v[114:117], v[170:173], v[182:185], v[114:117]
	v_mfma_f32_16x16x32_bf16 v[106:109], v[160:163], v[192:195], v[106:109]
	v_mfma_f32_16x16x32_bf16 v[98:101], v[170:173], v[192:195], v[98:101]
	v_mfma_f32_16x16x32_bf16 v[90:93], v[160:163], v[200:203], v[90:93]
	v_mfma_f32_16x16x32_bf16 v[82:85], v[170:173], v[200:203], v[82:85]
	v_mfma_f32_16x16x32_bf16 v[74:77], v[160:163], v[208:211], v[74:77]
	v_mfma_f32_16x16x32_bf16 v[66:69], v[170:173], v[208:211], v[66:69]
	s_setprio 0
	s_barrier
	s_add_i32 s64, s64, s23
	s_mov_b32 m0, s64
	ds_read_b128 v[176:179], v186 offset:16384
	ds_read_b128 v[182:185], v186 offset:17408
	ds_read_b128 v[188:191], v186 offset:18432
	ds_read_b128 v[192:195], v186 offset:19456
	ds_read_b128 v[196:199], v186 offset:20480
	ds_read_b128 v[200:203], v186 offset:21504
	ds_read_b128 v[204:207], v186 offset:22528
	ds_read_b128 v[208:211], v186 offset:23552
	global_load_lds_dwordx4 v0, s[46:47]
	s_add_i32 m0, s64, 0x2000
	s_add_u32 s64, s46, 0x40000
	s_addc_u32 s65, s47, 0
	s_add_i32 s68, s68, s23
	global_load_lds_dwordx4 v146, s[46:47]
	s_mov_b32 m0, s68
	s_nop 0
	global_load_lds_dwordx4 v0, s[64:65]
	s_add_i32 m0, s68, 0x2000
	s_nop 0
	global_load_lds_dwordx4 v146, s[64:65]
	s_mov_b32 m0, s51
	s_nop 0
	global_load_lds_dwordx4 v150, s[48:49]
	s_mov_b32 m0, s52
	s_nop 0
	global_load_lds_dwordx4 v148, s[48:49]
	s_waitcnt vmcnt(8)
	s_waitcnt lgkmcnt(0)
	s_barrier
	s_setprio 1
	s_waitcnt lgkmcnt(0)
	v_mfma_f32_16x16x32_bf16 v[62:65], v[130:133], v[176:179], v[62:65]
	v_mfma_f32_16x16x32_bf16 v[54:57], v[138:141], v[176:179], v[54:57]
	v_mfma_f32_16x16x32_bf16 v[46:49], v[130:133], v[188:191], v[46:49]
	v_mfma_f32_16x16x32_bf16 v[38:41], v[138:141], v[188:191], v[38:41]
	v_mfma_f32_16x16x32_bf16 v[30:33], v[130:133], v[196:199], v[30:33]
	v_mfma_f32_16x16x32_bf16 v[22:25], v[138:141], v[196:199], v[22:25]
	v_mfma_f32_16x16x32_bf16 v[14:17], v[130:133], v[204:207], v[14:17]
	v_mfma_f32_16x16x32_bf16 v[6:9], v[138:141], v[204:207], v[6:9]
	v_mfma_f32_16x16x32_bf16 v[62:65], v[134:137], v[182:185], v[62:65]
	v_mfma_f32_16x16x32_bf16 v[54:57], v[142:145], v[182:185], v[54:57]
	v_mfma_f32_16x16x32_bf16 v[46:49], v[134:137], v[192:195], v[46:49]
	v_mfma_f32_16x16x32_bf16 v[38:41], v[142:145], v[192:195], v[38:41]
	v_mfma_f32_16x16x32_bf16 v[30:33], v[134:137], v[200:203], v[30:33]
	v_mfma_f32_16x16x32_bf16 v[22:25], v[142:145], v[200:203], v[22:25]
	v_mfma_f32_16x16x32_bf16 v[14:17], v[134:137], v[208:211], v[14:17]
	v_mfma_f32_16x16x32_bf16 v[6:9], v[142:145], v[208:211], v[6:9]
	v_mfma_f32_16x16x32_bf16 v[58:61], v[156:159], v[176:179], v[58:61]
	v_mfma_f32_16x16x32_bf16 v[50:53], v[164:167], v[176:179], v[50:53]
	v_mfma_f32_16x16x32_bf16 v[42:45], v[156:159], v[188:191], v[42:45]
	v_mfma_f32_16x16x32_bf16 v[34:37], v[164:167], v[188:191], v[34:37]
	v_mfma_f32_16x16x32_bf16 v[26:29], v[156:159], v[196:199], v[26:29]
	v_mfma_f32_16x16x32_bf16 v[18:21], v[164:167], v[196:199], v[18:21]
	v_mfma_f32_16x16x32_bf16 v[10:13], v[156:159], v[204:207], v[10:13]
	v_mfma_f32_16x16x32_bf16 v[2:5], v[164:167], v[204:207], v[2:5]
	v_mfma_f32_16x16x32_bf16 v[58:61], v[160:163], v[182:185], v[58:61]
	v_mfma_f32_16x16x32_bf16 v[50:53], v[170:173], v[182:185], v[50:53]
	v_mfma_f32_16x16x32_bf16 v[42:45], v[160:163], v[192:195], v[42:45]
	v_mfma_f32_16x16x32_bf16 v[34:37], v[170:173], v[192:195], v[34:37]
	v_mfma_f32_16x16x32_bf16 v[26:29], v[160:163], v[200:203], v[26:29]
	v_mfma_f32_16x16x32_bf16 v[18:21], v[170:173], v[200:203], v[18:21]
	v_mfma_f32_16x16x32_bf16 v[10:13], v[160:163], v[208:211], v[10:13]
	v_mfma_f32_16x16x32_bf16 v[2:5], v[170:173], v[208:211], v[2:5]
	s_setprio 0
	s_barrier
; #define PG8_STAGE(bufoff, gbase, voff) do { _Pragma("unroll") for (int _i = 0; _i < 2; ++_i) \
;         __builtin_amdgcn_global_load_lds((const unsigned*)((const char*)(gbase) + (voff)[_i]), (PG8_LAS unsigned*)(lds + (bufoff) + ldsw + _i * 8192), 16, 0, 0); } while (0)
; #define PG8_LDA(dst, b, h) do { _Pragma("unroll") for (int m = 0; m < 4; ++m) _Pragma("unroll") for (int k = 0; k < 2; ++k) dst[m][k] = *(const PG8_LAS bf16x8*)(lds + PG8_SA(b, h) + aoff + m * 2048 + k * 1024); } while (0)
; #define PG8_LDB(dst, b, h) do { _Pragma("unroll") for (int n = 0; n < 2; ++n) _Pragma("unroll") for (int k = 0; k < 2; ++k) dst[n][k] = *(const PG8_LAS bf16x8*)(lds + PG8_SB(b, h) + boff + n * 2048 + k * 1024); } while (0)
; #define PG8_MMA(ai, bj, At, Bt) do { __builtin_amdgcn_s_setprio(1); _Pragma("unroll") for (int m = 0; m < 4; ++m) _Pragma("unroll") for (int n = 0; n < 2; ++n) _Pragma("unroll") for (int k = 0; k < 2; ++k) \
;         acc[ai][bj][m][n] = __builtin_amdgcn_mfma_f32_16x16x32_bf16(Bt[n][k], At[m][k], acc[ai][bj][m][n], 0, 0, 0); __builtin_amdgcn_s_setprio(0); } while (0)
; #define PG8_WAIT_V(n) asm volatile("s_waitcnt vmcnt(" #n ")" ::: "memory")
; #define PG8_WAIT_L(n) asm volatile("s_waitcnt lgkmcnt(" #n ")" ::: "memory")
; #define PG8_BAR __builtin_amdgcn_s_barrier()
; #define PG8_SCHED __builtin_amdgcn_sched_barrier(0)
; template <class Epi, class Sched, bool ALIGN_EPI = false, bool SP2 = false, bool SPLITK = false>
; __device__ __forceinline__ void gemm_phase(PG8_LAS unsigned char* lds, const Gemm g, const Sched& S, const Epi& E) {
;     ...
;             PG8_LDB(B0, 1, 0); PG8_LDB(B1, 1, 1); PG8_SCHED; PG8_LDA(At, 1, 0); PG8_STAGE(PG8_SA(0, 1), a2 + hstep, voffA);
;             PG8_WAIT_V(8); PG8_WAIT_L(0); PG8_BAR; PG8_MMA(0, 0, At, B0); PG8_MMA(0, 1, At, B1); PG8_BAR; PG8_SCHED;
;             PG8_LDA(At, 1, 1); PG8_STAGE(PG8_SB(1, 0), b3, voffB); PG8_STAGE(PG8_SB(1, 1), b3 + hstep, voffB); PG8_STAGE(PG8_SA(1, 0), a3, voffA);
;             PG8_WAIT_V(8); PG8_WAIT_L(0); PG8_BAR; PG8_MMA(1, 0, At, B0); PG8_MMA(1, 1, At, B1); PG8_BAR; PG8_SCHED;
	s_add_i32 s64, 0, 0x18000
	s_add_i32 s65, 0, 0x1c000
	v_add_u32_e32 v142, s64, v181
	v_add_u32_e32 v168, s65, v181
	ds_read_b128 v[130:133], v142
	ds_read_b128 v[134:137], v142 offset:1024
	ds_read_b128 v[138:141], v142 offset:2048
	ds_read_b128 v[142:145], v142 offset:3072
	ds_read_b128 v[156:159], v168
	ds_read_b128 v[160:163], v168 offset:1024
	ds_read_b128 v[164:167], v168 offset:2048
	ds_read_b128 v[170:173], v168 offset:3072
	s_add_u32 vcc_lo, s48, 0x80
	s_addc_u32 vcc_hi, s49, 0
	s_add_u32 s48, s48, 0x40000
	s_addc_u32 s49, s49, 0
	s_mov_b32 m0, s53
	ds_read_b128 v[176:179], v186 offset:32768
	ds_read_b128 v[182:185], v186 offset:33792
	ds_read_b128 v[188:191], v186 offset:34816
	ds_read_b128 v[192:195], v186 offset:35840
	ds_read_b128 v[196:199], v186 offset:36864
	ds_read_b128 v[200:203], v186 offset:37888
	ds_read_b128 v[204:207], v186 offset:38912
	ds_read_b128 v[208:211], v186 offset:39936
	global_load_lds_dwordx4 v150, s[48:49]
	s_mov_b32 m0, s54
	s_nop 0
	global_load_lds_dwordx4 v148, s[48:49]
	s_waitcnt vmcnt(8)
	s_waitcnt lgkmcnt(0)
	s_barrier
	s_setprio 1
	s_waitcnt lgkmcnt(0)
	v_mfma_f32_16x16x32_bf16 v[126:129], v[130:133], v[176:179], v[126:129]
	v_mfma_f32_16x16x32_bf16 v[118:121], v[138:141], v[176:179], v[118:121]
	v_mfma_f32_16x16x32_bf16 v[110:113], v[130:133], v[188:191], v[110:113]
	v_mfma_f32_16x16x32_bf16 v[102:105], v[138:141], v[188:191], v[102:105]
	v_mfma_f32_16x16x32_bf16 v[94:97], v[130:133], v[196:199], v[94:97]
	v_mfma_f32_16x16x32_bf16 v[86:89], v[138:141], v[196:199], v[86:89]
	v_mfma_f32_16x16x32_bf16 v[78:81], v[130:133], v[204:207], v[78:81]
	v_mfma_f32_16x16x32_bf16 v[70:73], v[138:141], v[204:207], v[70:73]
	v_mfma_f32_16x16x32_bf16 v[126:129], v[134:137], v[182:185], v[126:129]
	v_mfma_f32_16x16x32_bf16 v[118:121], v[142:145], v[182:185], v[118:121]
	v_mfma_f32_16x16x32_bf16 v[110:113], v[134:137], v[192:195], v[110:113]
	v_mfma_f32_16x16x32_bf16 v[102:105], v[142:145], v[192:195], v[102:105]
	v_mfma_f32_16x16x32_bf16 v[94:97], v[134:137], v[200:203], v[94:97]
	v_mfma_f32_16x16x32_bf16 v[86:89], v[142:145], v[200:203], v[86:89]
	v_mfma_f32_16x16x32_bf16 v[78:81], v[134:137], v[208:211], v[78:81]
	v_mfma_f32_16x16x32_bf16 v[70:73], v[142:145], v[208:211], v[70:73]
	v_mfma_f32_16x16x32_bf16 v[122:125], v[156:159], v[176:179], v[122:125]
	v_mfma_f32_16x16x32_bf16 v[114:117], v[164:167], v[176:179], v[114:117]
	v_mfma_f32_16x16x32_bf16 v[106:109], v[156:159], v[188:191], v[106:109]
	v_mfma_f32_16x16x32_bf16 v[98:101], v[164:167], v[188:191], v[98:101]
	v_mfma_f32_16x16x32_bf16 v[90:93], v[156:159], v[196:199], v[90:93]
	v_mfma_f32_16x16x32_bf16 v[82:85], v[164:167], v[196:199], v[82:85]
	v_mfma_f32_16x16x32_bf16 v[74:77], v[156:159], v[204:207], v[74:77]
	v_mfma_f32_16x16x32_bf16 v[66:69], v[164:167], v[204:207], v[66:69]
	v_mfma_f32_16x16x32_bf16 v[122:125], v[160:163], v[182:185], v[122:125]
	v_mfma_f32_16x16x32_bf16 v[114:117], v[170:173], v[182:185], v[114:117]
	v_mfma_f32_16x16x32_bf16 v[106:109], v[160:163], v[192:195], v[106:109]
	v_mfma_f32_16x16x32_bf16 v[98:101], v[170:173], v[192:195], v[98:101]
	v_mfma_f32_16x16x32_bf16 v[90:93], v[160:163], v[200:203], v[90:93]
	v_mfma_f32_16x16x32_bf16 v[82:85], v[170:173], v[200:203], v[82:85]
	v_mfma_f32_16x16x32_bf16 v[74:77], v[160:163], v[208:211], v[74:77]
	v_mfma_f32_16x16x32_bf16 v[66:69], v[170:173], v[208:211], v[66:69]
	s_setprio 0
	s_barrier
	s_add_i32 s48, s64, s23
	s_add_u32 s46, s46, 0x80
	s_addc_u32 s47, s47, 0
	s_mov_b32 m0, s48
	ds_read_b128 v[176:179], v186 offset:49152
	ds_read_b128 v[182:185], v186 offset:50176
	ds_read_b128 v[188:191], v186 offset:51200
	ds_read_b128 v[192:195], v186 offset:52224
	ds_read_b128 v[196:199], v186 offset:53248
	ds_read_b128 v[200:203], v186 offset:54272
	ds_read_b128 v[204:207], v186 offset:55296
	ds_read_b128 v[208:211], v186 offset:56320
	global_load_lds_dwordx4 v0, s[46:47]
	s_add_i32 m0, s48, 0x2000
	s_add_i32 s48, s65, s23
	global_load_lds_dwordx4 v146, s[46:47]
	s_add_u32 s46, s46, 0x40000
	s_addc_u32 s47, s47, 0
	s_mov_b32 m0, s48
	s_nop 0
	global_load_lds_dwordx4 v0, s[46:47]
	s_add_i32 m0, s48, 0x2000
	s_nop 0
	global_load_lds_dwordx4 v146, s[46:47]
	s_mov_b32 m0, s55
	s_nop 0
	global_load_lds_dwordx4 v150, vcc
	s_mov_b32 m0, s56
	s_nop 0
	global_load_lds_dwordx4 v148, vcc
	s_waitcnt vmcnt(8)
	s_waitcnt lgkmcnt(0)
	s_barrier
	s_setprio 1
	s_waitcnt lgkmcnt(0)
	v_mfma_f32_16x16x32_bf16 v[62:65], v[130:133], v[176:179], v[62:65]
	v_mfma_f32_16x16x32_bf16 v[54:57], v[138:141], v[176:179], v[54:57]
	v_mfma_f32_16x16x32_bf16 v[46:49], v[130:133], v[188:191], v[46:49]
	v_mfma_f32_16x16x32_bf16 v[38:41], v[138:141], v[188:191], v[38:41]
	v_mfma_f32_16x16x32_bf16 v[30:33], v[130:133], v[196:199], v[30:33]
	v_mfma_f32_16x16x32_bf16 v[22:25], v[138:141], v[196:199], v[22:25]
	v_mfma_f32_16x16x32_bf16 v[14:17], v[130:133], v[204:207], v[14:17]
	v_mfma_f32_16x16x32_bf16 v[6:9], v[138:141], v[204:207], v[6:9]
	v_mfma_f32_16x16x32_bf16 v[62:65], v[134:137], v[182:185], v[62:65]
	v_mfma_f32_16x16x32_bf16 v[54:57], v[142:145], v[182:185], v[54:57]
	v_mfma_f32_16x16x32_bf16 v[46:49], v[134:137], v[192:195], v[46:49]
	v_mfma_f32_16x16x32_bf16 v[38:41], v[142:145], v[192:195], v[38:41]
	v_mfma_f32_16x16x32_bf16 v[30:33], v[134:137], v[200:203], v[30:33]
	v_mfma_f32_16x16x32_bf16 v[22:25], v[142:145], v[200:203], v[22:25]
	v_mfma_f32_16x16x32_bf16 v[14:17], v[134:137], v[208:211], v[14:17]
	v_mfma_f32_16x16x32_bf16 v[6:9], v[142:145], v[208:211], v[6:9]
	v_mfma_f32_16x16x32_bf16 v[58:61], v[156:159], v[176:179], v[58:61]
	v_mfma_f32_16x16x32_bf16 v[50:53], v[164:167], v[176:179], v[50:53]
	v_mfma_f32_16x16x32_bf16 v[42:45], v[156:159], v[188:191], v[42:45]
	v_mfma_f32_16x16x32_bf16 v[34:37], v[164:167], v[188:191], v[34:37]
	v_mfma_f32_16x16x32_bf16 v[26:29], v[156:159], v[196:199], v[26:29]
	v_mfma_f32_16x16x32_bf16 v[18:21], v[164:167], v[196:199], v[18:21]
	v_mfma_f32_16x16x32_bf16 v[10:13], v[156:159], v[204:207], v[10:13]
	v_mfma_f32_16x16x32_bf16 v[2:5], v[164:167], v[204:207], v[2:5]
	v_mfma_f32_16x16x32_bf16 v[58:61], v[160:163], v[182:185], v[58:61]
	v_mfma_f32_16x16x32_bf16 v[50:53], v[170:173], v[182:185], v[50:53]
	v_mfma_f32_16x16x32_bf16 v[42:45], v[160:163], v[192:195], v[42:45]
	v_mfma_f32_16x16x32_bf16 v[34:37], v[170:173], v[192:195], v[34:37]
	v_mfma_f32_16x16x32_bf16 v[26:29], v[160:163], v[200:203], v[26:29]
	v_mfma_f32_16x16x32_bf16 v[18:21], v[170:173], v[200:203], v[18:21]
	v_mfma_f32_16x16x32_bf16 v[10:13], v[160:163], v[208:211], v[10:13]
	v_mfma_f32_16x16x32_bf16 v[2:5], v[170:173], v[208:211], v[2:5]
	s_setprio 0
	s_barrier
	s_add_i32 s45, s45, 2
	s_add_u32 s42, s42, 0x100
	s_addc_u32 s43, s43, 0
	s_add_u32 s25, s25, 0x100
	s_addc_u32 s41, s41, 0
	s_cmp_gt_u32 s45, 13
	s_cbranch_scc0 .LBB0_582
	s_and_b64 vcc, exec, s[16:17]
	s_cbranch_vccz .LBB0_585
	s_barrier

; #define PG8_STAGE(bufoff, gbase, voff) do { _Pragma("unroll") for (int _i = 0; _i < 2; ++_i) \
;         __builtin_amdgcn_global_load_lds((const unsigned*)((const char*)(gbase) + (voff)[_i]), (PG8_LAS unsigned*)(lds + (bufoff) + ldsw + _i * 8192), 16, 0, 0); } while (0)
; #define PG8_LDA(dst, b, h) do { _Pragma("unroll") for (int m = 0; m < 4; ++m) _Pragma("unroll") for (int k = 0; k < 2; ++k) dst[m][k] = *(const PG8_LAS bf16x8*)(lds + PG8_SA(b, h) + aoff + m * 2048 + k * 1024); } while (0)
; #define PG8_LDB(dst, b, h) do { _Pragma("unroll") for (int n = 0; n < 2; ++n) _Pragma("unroll") for (int k = 0; k < 2; ++k) dst[n][k] = *(const PG8_LAS bf16x8*)(lds + PG8_SB(b, h) + boff + n * 2048 + k * 1024); } while (0)
; #define PG8_WAIT_V(n) asm volatile("s_waitcnt vmcnt(" #n ")" ::: "memory")
; #define PG8_WAIT_L(n) asm volatile("s_waitcnt lgkmcnt(" #n ")" ::: "memory")
; #define PG8_BAR __builtin_amdgcn_s_barrier()
; #define PG8_SCHED __builtin_amdgcn_sched_barrier(0)
; template <class Epi, class Sched, bool ALIGN_EPI = false, bool SP2 = false, bool SPLITK = false>
; __device__ __forceinline__ void gemm_phase(PG8_LAS unsigned char* lds, const Gemm g, const Sched& S, const Epi& E) {
;     ...
;         const char* nA = has_next ? (const char*)g.A + (size_t)nxt.pm * tstep : cA; const char* nB = has_next ? (const char*)g.Bt + (size_t)nxt.pn * tstep : cB;
;         for (int t = 0; t < nt; t += 2) {
;             const bool last = (t == nt - 2);
;             if constexpr (SPLITK) { if (t == nt1) E.mid(acc, cur, wr, wc, fr, fq); }
;             const char* a1 = PG8_TA(t + 1);
;             const char* a2 = last ? nA : PG8_TA(t + 2); const char* b2 = last ? nB : PG8_TB(t + 2);
;             const char* a3 = a2 + kstep; const char* b3 = b2 + kstep;
;             if (last && has_next) S.a_ready(nxt);
;             if constexpr (SP2) {
;             PG8_LDB(B0, 0, 0); PG8_LDB(B1, 0, 1); PG8_SCHED; PG8_LDA(At, 0, 0); PG8_STAGE(PG8_SA(1, 1), a1 + hstep, voffA);
;             PG8_WAIT_V(8); PG8_WAIT_L(0); PG8_BAR; PG8_MMA(0, 0, At, B0); PG8_MMA(0, 1, At, B1); PG8_BAR; PG8_SCHED;
;             PG8_LDA(At, 0, 1); PG8_STAGE(PG8_SB(0, 0), b2, voffB); PG8_STAGE(PG8_SB(0, 1), b2 + hstep, voffB); PG8_STAGE(PG8_SA(0, 0), a2, voffA);
;             PG8_WAIT_V(8); PG8_WAIT_L(0); PG8_BAR; PG8_MMA(1, 0, At, B0); PG8_MMA(1, 1, At, B1); PG8_BAR; PG8_SCHED;
.LBB0_701:
	s_add_u32 s40, s42, 0x100
	s_addc_u32 s41, s43, 0
	s_add_i32 s58, 0, 0x10000
	s_cmp_eq_u32 s57, 40
	s_cselect_b32 s49, s35, s41
	s_cselect_b32 s48, s34, s40
	s_cselect_b32 s47, s37, s45
	s_cselect_b32 s46, s36, s12
	s_add_i32 s59, 0, 0x14000
	v_add_u32_e32 v118, s58, v224
	v_add_u32_e32 v150, s59, v224
	ds_read_b128 v[82:85], v118
	ds_read_b128 v[94:97], v118 offset:1024
	ds_read_b128 v[106:109], v118 offset:2048
	ds_read_b128 v[118:121], v118 offset:3072
	ds_read_b128 v[130:133], v150
	ds_read_b128 v[142:145], v150 offset:1024
	ds_read_b128 v[146:149], v150 offset:2048
	ds_read_b128 v[150:153], v150 offset:3072
	s_add_i32 m0, s24, 0xc000
	ds_read_b128 v[162:165], v225
	ds_read_b128 v[166:169], v225 offset:1024
	ds_read_b128 v[170:173], v225 offset:2048
	ds_read_b128 v[174:177], v225 offset:3072
	ds_read_b128 v[178:181], v225 offset:4096
	ds_read_b128 v[182:185], v225 offset:5120
	ds_read_b128 v[186:189], v225 offset:6144
	ds_read_b128 v[190:193], v225 offset:7168
	global_load_lds_dwordx4 v200, s[42:43]
	s_add_i32 m0, s24, 0xe000
	s_nop 0
	global_load_lds_dwordx4 v202, s[42:43]
	s_waitcnt vmcnt(8)
	s_waitcnt lgkmcnt(0)
	s_barrier
	s_setprio 1
	s_waitcnt lgkmcnt(0)
	v_mfma_f32_16x16x32_bf16 v[158:161], v[82:85], v[162:165], v[158:161]
	v_mfma_f32_16x16x32_bf16 v[154:157], v[106:109], v[162:165], v[154:157]
	v_mfma_f32_16x16x32_bf16 v[126:129], v[82:85], v[170:173], v[126:129]
	v_mfma_f32_16x16x32_bf16 v[122:125], v[106:109], v[170:173], v[122:125]
	v_mfma_f32_16x16x32_bf16 v[102:105], v[82:85], v[178:181], v[102:105]
	v_mfma_f32_16x16x32_bf16 v[98:101], v[106:109], v[178:181], v[98:101]
	v_mfma_f32_16x16x32_bf16 v[78:81], v[82:85], v[186:189], v[78:81]
	v_mfma_f32_16x16x32_bf16 v[74:77], v[106:109], v[186:189], v[74:77]
	v_mfma_f32_16x16x32_bf16 v[158:161], v[94:97], v[166:169], v[158:161]
	v_mfma_f32_16x16x32_bf16 v[154:157], v[118:121], v[166:169], v[154:157]
	v_mfma_f32_16x16x32_bf16 v[126:129], v[94:97], v[174:177], v[126:129]
	v_mfma_f32_16x16x32_bf16 v[122:125], v[118:121], v[174:177], v[122:125]
	v_mfma_f32_16x16x32_bf16 v[102:105], v[94:97], v[182:185], v[102:105]
	v_mfma_f32_16x16x32_bf16 v[98:101], v[118:121], v[182:185], v[98:101]
	v_mfma_f32_16x16x32_bf16 v[78:81], v[94:97], v[190:193], v[78:81]
	v_mfma_f32_16x16x32_bf16 v[74:77], v[118:121], v[190:193], v[74:77]
	v_mfma_f32_16x16x32_bf16 v[138:141], v[130:133], v[162:165], v[138:141]
	v_mfma_f32_16x16x32_bf16 v[134:137], v[146:149], v[162:165], v[134:137]
	v_mfma_f32_16x16x32_bf16 v[114:117], v[130:133], v[170:173], v[114:117]
	v_mfma_f32_16x16x32_bf16 v[110:113], v[146:149], v[170:173], v[110:113]
	v_mfma_f32_16x16x32_bf16 v[90:93], v[130:133], v[178:181], v[90:93]
	v_mfma_f32_16x16x32_bf16 v[86:89], v[146:149], v[178:181], v[86:89]
	v_mfma_f32_16x16x32_bf16 v[70:73], v[130:133], v[186:189], v[70:73]
	v_mfma_f32_16x16x32_bf16 v[66:69], v[146:149], v[186:189], v[66:69]
	v_mfma_f32_16x16x32_bf16 v[138:141], v[142:145], v[166:169], v[138:141]
	v_mfma_f32_16x16x32_bf16 v[134:137], v[150:153], v[166:169], v[134:137]
	v_mfma_f32_16x16x32_bf16 v[114:117], v[142:145], v[174:177], v[114:117]
	v_mfma_f32_16x16x32_bf16 v[110:113], v[150:153], v[174:177], v[110:113]
	v_mfma_f32_16x16x32_bf16 v[90:93], v[142:145], v[182:185], v[90:93]
	v_mfma_f32_16x16x32_bf16 v[86:89], v[150:153], v[182:185], v[86:89]
	v_mfma_f32_16x16x32_bf16 v[70:73], v[142:145], v[190:193], v[70:73]
	v_mfma_f32_16x16x32_bf16 v[66:69], v[150:153], v[190:193], v[66:69]
	s_setprio 0
	s_barrier
	s_add_i32 s42, s58, s23
	s_mov_b32 m0, s42
	ds_read_b128 v[162:165], v225 offset:16384
	ds_read_b128 v[166:169], v225 offset:17408
	ds_read_b128 v[170:173], v225 offset:18432
	ds_read_b128 v[174:177], v225 offset:19456
	ds_read_b128 v[178:181], v225 offset:20480
	ds_read_b128 v[182:185], v225 offset:21504
	ds_read_b128 v[186:189], v225 offset:22528
	ds_read_b128 v[190:193], v225 offset:23552
	global_load_lds_dwordx4 v0, s[46:47]
	s_add_i32 m0, s42, 0x2000
	s_add_u32 s42, s46, 0xb0000
	s_addc_u32 s43, s47, 0
	s_add_i32 s58, s59, s23
	global_load_lds_dwordx4 v198, s[46:47]
	s_mov_b32 m0, s58
	s_nop 0
	global_load_lds_dwordx4 v0, s[42:43]
	s_add_i32 m0, s58, 0x2000
	s_nop 0
	global_load_lds_dwordx4 v198, s[42:43]
	s_mov_b32 m0, s24
	s_nop 0
	global_load_lds_dwordx4 v194, s[48:49]
	s_mov_b32 m0, s25
	s_nop 0
	global_load_lds_dwordx4 v196, s[48:49]
	s_waitcnt vmcnt(8)
	s_waitcnt lgkmcnt(0)
	s_barrier
	s_setprio 1
	s_waitcnt lgkmcnt(0)
	v_mfma_f32_16x16x32_bf16 v[62:65], v[82:85], v[162:165], v[62:65]
	v_mfma_f32_16x16x32_bf16 v[58:61], v[106:109], v[162:165], v[58:61]
	v_mfma_f32_16x16x32_bf16 v[46:49], v[82:85], v[170:173], v[46:49]
	v_mfma_f32_16x16x32_bf16 v[42:45], v[106:109], v[170:173], v[42:45]
	v_mfma_f32_16x16x32_bf16 v[30:33], v[82:85], v[178:181], v[30:33]
	v_mfma_f32_16x16x32_bf16 v[26:29], v[106:109], v[178:181], v[26:29]
	v_mfma_f32_16x16x32_bf16 v[14:17], v[82:85], v[186:189], v[14:17]
	v_mfma_f32_16x16x32_bf16 v[10:13], v[106:109], v[186:189], v[10:13]
	v_mfma_f32_16x16x32_bf16 v[62:65], v[94:97], v[166:169], v[62:65]
	v_mfma_f32_16x16x32_bf16 v[58:61], v[118:121], v[166:169], v[58:61]
	v_mfma_f32_16x16x32_bf16 v[46:49], v[94:97], v[174:177], v[46:49]
	v_mfma_f32_16x16x32_bf16 v[42:45], v[118:121], v[174:177], v[42:45]
	v_mfma_f32_16x16x32_bf16 v[30:33], v[94:97], v[182:185], v[30:33]
	v_mfma_f32_16x16x32_bf16 v[26:29], v[118:121], v[182:185], v[26:29]
	v_mfma_f32_16x16x32_bf16 v[14:17], v[94:97], v[190:193], v[14:17]
	v_mfma_f32_16x16x32_bf16 v[10:13], v[118:121], v[190:193], v[10:13]
	v_mfma_f32_16x16x32_bf16 v[54:57], v[130:133], v[162:165], v[54:57]
	v_mfma_f32_16x16x32_bf16 v[50:53], v[146:149], v[162:165], v[50:53]
	v_mfma_f32_16x16x32_bf16 v[38:41], v[130:133], v[170:173], v[38:41]
	v_mfma_f32_16x16x32_bf16 v[34:37], v[146:149], v[170:173], v[34:37]
	v_mfma_f32_16x16x32_bf16 v[22:25], v[130:133], v[178:181], v[22:25]
	v_mfma_f32_16x16x32_bf16 v[18:21], v[146:149], v[178:181], v[18:21]
	v_mfma_f32_16x16x32_bf16 v[6:9], v[130:133], v[186:189], v[6:9]
	v_mfma_f32_16x16x32_bf16 v[2:5], v[146:149], v[186:189], v[2:5]
	v_mfma_f32_16x16x32_bf16 v[54:57], v[142:145], v[166:169], v[54:57]
	v_mfma_f32_16x16x32_bf16 v[50:53], v[150:153], v[166:169], v[50:53]
	v_mfma_f32_16x16x32_bf16 v[38:41], v[142:145], v[174:177], v[38:41]
	v_mfma_f32_16x16x32_bf16 v[34:37], v[150:153], v[174:177], v[34:37]
	v_mfma_f32_16x16x32_bf16 v[22:25], v[142:145], v[182:185], v[22:25]
	v_mfma_f32_16x16x32_bf16 v[18:21], v[150:153], v[182:185], v[18:21]
	v_mfma_f32_16x16x32_bf16 v[6:9], v[142:145], v[190:193], v[6:9]
	v_mfma_f32_16x16x32_bf16 v[2:5], v[150:153], v[190:193], v[2:5]
	s_setprio 0
	s_barrier
; #define PG8_STAGE(bufoff, gbase, voff) do { _Pragma("unroll") for (int _i = 0; _i < 2; ++_i) \
;         __builtin_amdgcn_global_load_lds((const unsigned*)((const char*)(gbase) + (voff)[_i]), (PG8_LAS unsigned*)(lds + (bufoff) + ldsw + _i * 8192), 16, 0, 0); } while (0)
; #define PG8_LDA(dst, b, h) do { _Pragma("unroll") for (int m = 0; m < 4; ++m) _Pragma("unroll") for (int k = 0; k < 2; ++k) dst[m][k] = *(const PG8_LAS bf16x8*)(lds + PG8_SA(b, h) + aoff + m * 2048 + k * 1024); } while (0)
; #define PG8_LDB(dst, b, h) do { _Pragma("unroll") for (int n = 0; n < 2; ++n) _Pragma("unroll") for (int k = 0; k < 2; ++k) dst[n][k] = *(const PG8_LAS bf16x8*)(lds + PG8_SB(b, h) + boff + n * 2048 + k * 1024); } while (0)
; #define PG8_MMA(ai, bj, At, Bt) do { __builtin_amdgcn_s_setprio(1); _Pragma("unroll") for (int m = 0; m < 4; ++m) _Pragma("unroll") for (int n = 0; n < 2; ++n) _Pragma("unroll") for (int k = 0; k < 2; ++k) \
;         acc[ai][bj][m][n] = __builtin_amdgcn_mfma_f32_16x16x32_bf16(Bt[n][k], At[m][k], acc[ai][bj][m][n], 0, 0, 0); __builtin_amdgcn_s_setprio(0); } while (0)
; #define PG8_WAIT_V(n) asm volatile("s_waitcnt vmcnt(" #n ")" ::: "memory")
; #define PG8_WAIT_L(n) asm volatile("s_waitcnt lgkmcnt(" #n ")" ::: "memory")
; #define PG8_BAR __builtin_amdgcn_s_barrier()
; #define PG8_SCHED __builtin_amdgcn_sched_barrier(0)
; template <class Epi, class Sched, bool ALIGN_EPI = false, bool SP2 = false, bool SPLITK = false>
; __device__ __forceinline__ void gemm_phase(PG8_LAS unsigned char* lds, const Gemm g, const Sched& S, const Epi& E) {
;     ...
;             PG8_LDB(B0, 1, 0); PG8_LDB(B1, 1, 1); PG8_SCHED; PG8_LDA(At, 1, 0); PG8_STAGE(PG8_SA(0, 1), a2 + hstep, voffA);
;             PG8_WAIT_V(8); PG8_WAIT_L(0); PG8_BAR; PG8_MMA(0, 0, At, B0); PG8_MMA(0, 1, At, B1); PG8_BAR; PG8_SCHED;
;             PG8_LDA(At, 1, 1); PG8_STAGE(PG8_SB(1, 0), b3, voffB); PG8_STAGE(PG8_SB(1, 1), b3 + hstep, voffB); PG8_STAGE(PG8_SA(1, 0), a3, voffA);
;             PG8_WAIT_V(8); PG8_WAIT_L(0); PG8_BAR; PG8_MMA(1, 0, At, B0); PG8_MMA(1, 1, At, B1); PG8_BAR; PG8_SCHED;
	s_add_i32 s58, 0, 0x18000
	s_add_i32 s59, 0, 0x1c000
	v_add_u32_e32 v118, s58, v224
	v_add_u32_e32 v150, s59, v224
	ds_read_b128 v[82:85], v118
	ds_read_b128 v[94:97], v118 offset:1024
	ds_read_b128 v[106:109], v118 offset:2048
	ds_read_b128 v[118:121], v118 offset:3072
	ds_read_b128 v[130:133], v150
	ds_read_b128 v[142:145], v150 offset:1024
	ds_read_b128 v[146:149], v150 offset:2048
	ds_read_b128 v[150:153], v150 offset:3072
	s_add_u32 s42, s48, 0xb0000
	s_addc_u32 s43, s49, 0
	s_mov_b32 m0, s33
	ds_read_b128 v[162:165], v225 offset:32768
	ds_read_b128 v[166:169], v225 offset:33792
	ds_read_b128 v[170:173], v225 offset:34816
	ds_read_b128 v[174:177], v225 offset:35840
	ds_read_b128 v[178:181], v225 offset:36864
	ds_read_b128 v[182:185], v225 offset:37888
	ds_read_b128 v[186:189], v225 offset:38912
	ds_read_b128 v[190:193], v225 offset:39936
	global_load_lds_dwordx4 v194, s[42:43]
	s_mov_b32 m0, s50
	s_nop 0
	global_load_lds_dwordx4 v196, s[42:43]
	s_waitcnt vmcnt(8)
	s_waitcnt lgkmcnt(0)
	s_barrier
	s_setprio 1
	s_waitcnt lgkmcnt(0)
	v_mfma_f32_16x16x32_bf16 v[158:161], v[82:85], v[162:165], v[158:161]
	v_mfma_f32_16x16x32_bf16 v[154:157], v[106:109], v[162:165], v[154:157]
	v_mfma_f32_16x16x32_bf16 v[126:129], v[82:85], v[170:173], v[126:129]
	v_mfma_f32_16x16x32_bf16 v[122:125], v[106:109], v[170:173], v[122:125]
	v_mfma_f32_16x16x32_bf16 v[102:105], v[82:85], v[178:181], v[102:105]
	v_mfma_f32_16x16x32_bf16 v[98:101], v[106:109], v[178:181], v[98:101]
	v_mfma_f32_16x16x32_bf16 v[78:81], v[82:85], v[186:189], v[78:81]
	v_mfma_f32_16x16x32_bf16 v[74:77], v[106:109], v[186:189], v[74:77]
	v_mfma_f32_16x16x32_bf16 v[158:161], v[94:97], v[166:169], v[158:161]
	v_mfma_f32_16x16x32_bf16 v[154:157], v[118:121], v[166:169], v[154:157]
	v_mfma_f32_16x16x32_bf16 v[126:129], v[94:97], v[174:177], v[126:129]
	v_mfma_f32_16x16x32_bf16 v[122:125], v[118:121], v[174:177], v[122:125]
	v_mfma_f32_16x16x32_bf16 v[102:105], v[94:97], v[182:185], v[102:105]
	v_mfma_f32_16x16x32_bf16 v[98:101], v[118:121], v[182:185], v[98:101]
	v_mfma_f32_16x16x32_bf16 v[78:81], v[94:97], v[190:193], v[78:81]
	v_mfma_f32_16x16x32_bf16 v[74:77], v[118:121], v[190:193], v[74:77]
	v_mfma_f32_16x16x32_bf16 v[138:141], v[130:133], v[162:165], v[138:141]
	v_mfma_f32_16x16x32_bf16 v[134:137], v[146:149], v[162:165], v[134:137]
	v_mfma_f32_16x16x32_bf16 v[114:117], v[130:133], v[170:173], v[114:117]
	v_mfma_f32_16x16x32_bf16 v[110:113], v[146:149], v[170:173], v[110:113]
	v_mfma_f32_16x16x32_bf16 v[90:93], v[130:133], v[178:181], v[90:93]
	v_mfma_f32_16x16x32_bf16 v[86:89], v[146:149], v[178:181], v[86:89]
	v_mfma_f32_16x16x32_bf16 v[70:73], v[130:133], v[186:189], v[70:73]
	v_mfma_f32_16x16x32_bf16 v[66:69], v[146:149], v[186:189], v[66:69]
	v_mfma_f32_16x16x32_bf16 v[138:141], v[142:145], v[166:169], v[138:141]
	v_mfma_f32_16x16x32_bf16 v[134:137], v[150:153], v[166:169], v[134:137]
	v_mfma_f32_16x16x32_bf16 v[114:117], v[142:145], v[174:177], v[114:117]
	v_mfma_f32_16x16x32_bf16 v[110:113], v[150:153], v[174:177], v[110:113]
	v_mfma_f32_16x16x32_bf16 v[90:93], v[142:145], v[182:185], v[90:93]
	v_mfma_f32_16x16x32_bf16 v[86:89], v[150:153], v[182:185], v[86:89]
	v_mfma_f32_16x16x32_bf16 v[70:73], v[142:145], v[190:193], v[70:73]
	v_mfma_f32_16x16x32_bf16 v[66:69], v[150:153], v[190:193], v[66:69]
	s_setprio 0
	s_barrier
	s_add_i32 s42, s58, s23
	s_add_u32 vcc_lo, s46, 0x80
	s_addc_u32 vcc_hi, s47, 0
	s_mov_b32 m0, s42
	ds_read_b128 v[162:165], v225 offset:49152
	ds_read_b128 v[166:169], v225 offset:50176
	ds_read_b128 v[170:173], v225 offset:51200
	ds_read_b128 v[174:177], v225 offset:52224
	ds_read_b128 v[178:181], v225 offset:53248
	ds_read_b128 v[182:185], v225 offset:54272
	ds_read_b128 v[186:189], v225 offset:55296
	ds_read_b128 v[190:193], v225 offset:56320
	global_load_lds_dwordx4 v0, vcc
	s_add_i32 m0, s42, 0x2000
	s_add_u32 s42, s46, 0xb0080
	s_addc_u32 s43, s47, 0
	s_add_i32 s46, s59, s23
	global_load_lds_dwordx4 v198, vcc
	s_mov_b32 m0, s46
	s_nop 0
	global_load_lds_dwordx4 v0, s[42:43]
	s_add_i32 m0, s46, 0x2000
	s_nop 0
	global_load_lds_dwordx4 v198, s[42:43]
	s_add_u32 vcc_lo, s48, 0x80
	s_addc_u32 vcc_hi, s49, 0
	s_mov_b32 m0, s51
	s_nop 0
	global_load_lds_dwordx4 v194, vcc
	s_mov_b32 m0, s52
	s_nop 0
	global_load_lds_dwordx4 v196, vcc
	s_waitcnt vmcnt(8)
	s_waitcnt lgkmcnt(0)
	s_barrier
	s_setprio 1
	s_waitcnt lgkmcnt(0)
	v_mfma_f32_16x16x32_bf16 v[62:65], v[82:85], v[162:165], v[62:65]
	v_mfma_f32_16x16x32_bf16 v[58:61], v[106:109], v[162:165], v[58:61]
	v_mfma_f32_16x16x32_bf16 v[46:49], v[82:85], v[170:173], v[46:49]
	v_mfma_f32_16x16x32_bf16 v[42:45], v[106:109], v[170:173], v[42:45]
	v_mfma_f32_16x16x32_bf16 v[30:33], v[82:85], v[178:181], v[30:33]
	v_mfma_f32_16x16x32_bf16 v[26:29], v[106:109], v[178:181], v[26:29]
	v_mfma_f32_16x16x32_bf16 v[14:17], v[82:85], v[186:189], v[14:17]
	v_mfma_f32_16x16x32_bf16 v[10:13], v[106:109], v[186:189], v[10:13]
	v_mfma_f32_16x16x32_bf16 v[62:65], v[94:97], v[166:169], v[62:65]
	v_mfma_f32_16x16x32_bf16 v[58:61], v[118:121], v[166:169], v[58:61]
	v_mfma_f32_16x16x32_bf16 v[46:49], v[94:97], v[174:177], v[46:49]
	v_mfma_f32_16x16x32_bf16 v[42:45], v[118:121], v[174:177], v[42:45]
	v_mfma_f32_16x16x32_bf16 v[30:33], v[94:97], v[182:185], v[30:33]
	v_mfma_f32_16x16x32_bf16 v[26:29], v[118:121], v[182:185], v[26:29]
	v_mfma_f32_16x16x32_bf16 v[14:17], v[94:97], v[190:193], v[14:17]
	v_mfma_f32_16x16x32_bf16 v[10:13], v[118:121], v[190:193], v[10:13]
	v_mfma_f32_16x16x32_bf16 v[54:57], v[130:133], v[162:165], v[54:57]
	v_mfma_f32_16x16x32_bf16 v[50:53], v[146:149], v[162:165], v[50:53]
	v_mfma_f32_16x16x32_bf16 v[38:41], v[130:133], v[170:173], v[38:41]
	v_mfma_f32_16x16x32_bf16 v[34:37], v[146:149], v[170:173], v[34:37]
	v_mfma_f32_16x16x32_bf16 v[22:25], v[130:133], v[178:181], v[22:25]
	v_mfma_f32_16x16x32_bf16 v[18:21], v[146:149], v[178:181], v[18:21]
	v_mfma_f32_16x16x32_bf16 v[6:9], v[130:133], v[186:189], v[6:9]
	v_mfma_f32_16x16x32_bf16 v[2:5], v[146:149], v[186:189], v[2:5]
	v_mfma_f32_16x16x32_bf16 v[54:57], v[142:145], v[166:169], v[54:57]
	v_mfma_f32_16x16x32_bf16 v[50:53], v[150:153], v[166:169], v[50:53]
	v_mfma_f32_16x16x32_bf16 v[38:41], v[142:145], v[174:177], v[38:41]
	v_mfma_f32_16x16x32_bf16 v[34:37], v[150:153], v[174:177], v[34:37]
	v_mfma_f32_16x16x32_bf16 v[22:25], v[142:145], v[182:185], v[22:25]
	v_mfma_f32_16x16x32_bf16 v[18:21], v[150:153], v[182:185], v[18:21]
	v_mfma_f32_16x16x32_bf16 v[6:9], v[142:145], v[190:193], v[6:9]
	v_mfma_f32_16x16x32_bf16 v[2:5], v[150:153], v[190:193], v[2:5]
	s_setprio 0
	s_barrier
	s_add_i32 s57, s57, 2
	s_add_u32 s12, s12, 0x100
	s_addc_u32 s45, s45, 0
	s_cmp_gt_u32 s57, 41
	s_mov_b64 s[42:43], s[40:41]
	s_cbranch_scc0 .LBB0_701
	s_and_b64 vcc, exec, s[18:19]
	s_cbranch_vccz .LBB0_704
	s_barrier
